# accumulate epilogue (x+=acc): next load group issued early into spare VGPR bank + counted vmcnt; weight-conversion item loops in GEMM tail slots (phases 2,6,9): all 8 row loads in flight
# speedup vs baseline: 1.0129x; 1.0050x over previous
.LBB0_421:
	s_mov_b32 s0, 0x2aaaaaab
	v_mul_hi_i32 v8, v38, s0
	v_lshrrev_b32_e32 v9, 31, v8
	v_ashrrev_i32_e32 v8, 3, v8
	v_add_u32_e32 v9, v8, v9
	s_movk_i32 s0, 0xfa00
	v_mad_u64_u32 v[10:11], s[0:1], v9, s0, v[6:7]
	v_lshlrev_b32_e32 v8, 6, v9
	v_ashrrev_i32_e32 v11, 31, v10
	v_lshl_add_u64 v[48:49], v[10:11], 2, v[2:3]
	v_or_b32_e32 v9, v8, v7
	v_mad_i64_i32 v[40:41], s[0:1], v9, s7, v[48:49]
	global_load_dwordx4 v[40:43], v[40:41], off
	v_or_b32_e32 v9, v8, v12
	v_mad_i64_i32 v[44:45], s[0:1], v9, s7, v[48:49]
	global_load_dwordx4 v[44:47], v[44:45], off
	v_or_b32_e32 v9, v8, v13
	v_add_u32_e32 v10, v10, v7
	v_ashrrev_i32_e32 v11, 31, v10
	v_add_u32_e32 v38, s8, v38
	v_add_u32_e32 v6, s6, v6
	v_mad_i64_i32 v[226:227], s[0:1], v9, s7, v[48:49]
	global_load_dwordx4 v[226:229], v[226:227], off
	v_or_b32_e32 v9, v8, v14
	v_mad_i64_i32 v[230:231], s[0:1], v9, s7, v[48:49]
	global_load_dwordx4 v[230:233], v[230:231], off
	v_or_b32_e32 v9, v8, v15
	v_mad_i64_i32 v[234:235], s[0:1], v9, s7, v[48:49]
	global_load_dwordx4 v[234:237], v[234:235], off
	v_or_b32_e32 v9, v8, v16
	v_mad_i64_i32 v[238:239], s[0:1], v9, s7, v[48:49]
	global_load_dwordx4 v[238:241], v[238:239], off
	v_or_b32_e32 v9, v8, v17
	v_mad_i64_i32 v[242:243], s[0:1], v9, s7, v[48:49]
	global_load_dwordx4 v[242:245], v[242:243], off
	v_or_b32_e32 v9, v8, v18
	v_mad_i64_i32 v[246:247], s[0:1], v9, s7, v[48:49]
	global_load_dwordx4 v[246:249], v[246:247], off
	v_ashrrev_i32_e32 v9, 31, v8
	v_lshl_add_u64 v[8:9], v[8:9], 1, v[4:5]
	s_movk_i32 s0, 0x17f
	v_cmp_lt_i32_e64 s[0:1], s0, v38
	s_or_b64 s[4:5], s[0:1], s[4:5]
	s_waitcnt vmcnt(7)
	ds_write2_b32 v23, v40, v41 offset1:1
	ds_write2_b32 v23, v42, v43 offset0:2 offset1:3
	s_waitcnt vmcnt(6)
	ds_write2_b32 v24, v44, v45 offset1:1
	ds_write2_b32 v25, v46, v47 offset1:1
	s_waitcnt vmcnt(5)
	ds_write2_b32 v26, v226, v227 offset1:1
	ds_write2_b32 v27, v228, v229 offset1:1
	s_waitcnt vmcnt(4)
	ds_write2_b32 v28, v230, v231 offset1:1
	ds_write2_b32 v29, v232, v233 offset1:1
	s_waitcnt lgkmcnt(7)
	s_waitcnt vmcnt(3)
	ds_write2_b32 v30, v234, v235 offset1:1
	ds_write2_b32 v31, v236, v237 offset1:1
	s_waitcnt vmcnt(2)
	ds_write2_b32 v32, v238, v239 offset1:1
	ds_write2_b32 v33, v240, v241 offset1:1
	s_waitcnt vmcnt(1)
	ds_write2_b32 v34, v242, v243 offset1:1
	ds_write2_b32 v35, v244, v245 offset1:1
	s_waitcnt vmcnt(0)
	ds_write2_b32 v36, v246, v247 offset1:1
	ds_write2_b32 v37, v248, v249 offset1:1
	s_waitcnt lgkmcnt(0)
	ds_read2_b32 v[40:41], v19 offset1:33
	s_waitcnt lgkmcnt(0)
	v_cvt_pk_bf16_f32 v40, v40, v41
	ds_read2_b32 v[42:43], v19 offset0:66 offset1:99
	s_waitcnt lgkmcnt(0)
	v_cvt_pk_bf16_f32 v41, v42, v43
	ds_read2_b32 v[42:43], v19 offset0:132 offset1:165
	s_waitcnt lgkmcnt(0)
	v_cvt_pk_bf16_f32 v42, v42, v43
	ds_read2_b32 v[44:45], v19 offset0:198 offset1:231
	s_waitcnt lgkmcnt(0)
	v_cvt_pk_bf16_f32 v43, v44, v45
	v_lshlrev_b64 v[44:45], 10, v[10:11]
	v_lshl_add_u64 v[44:45], v[8:9], 0, v[44:45]
	global_store_dwordx4 v[44:45], v[40:43], off
	ds_read2_b32 v[40:41], v19 offset0:8 offset1:41
	s_waitcnt lgkmcnt(0)
	v_cvt_pk_bf16_f32 v40, v40, v41
	ds_read2_b32 v[42:43], v19 offset0:74 offset1:107
	s_waitcnt lgkmcnt(0)
	v_cvt_pk_bf16_f32 v41, v42, v43
	ds_read2_b32 v[42:43], v19 offset0:140 offset1:173
	s_waitcnt lgkmcnt(0)
	v_cvt_pk_bf16_f32 v42, v42, v43
	ds_read2_b32 v[44:45], v19 offset0:206 offset1:239
	s_waitcnt lgkmcnt(0)
	v_cvt_pk_bf16_f32 v43, v44, v45
	v_add_u32_e32 v44, 8, v10
	v_ashrrev_i32_e32 v45, 31, v44
	v_lshlrev_b64 v[44:45], 10, v[44:45]
	v_lshl_add_u64 v[44:45], v[8:9], 0, v[44:45]
	global_store_dwordx4 v[44:45], v[40:43], off
	ds_read2_b32 v[40:41], v19 offset0:16 offset1:49
	s_waitcnt lgkmcnt(0)
	v_cvt_pk_bf16_f32 v40, v40, v41
	ds_read2_b32 v[42:43], v19 offset0:82 offset1:115
	s_waitcnt lgkmcnt(0)
	v_cvt_pk_bf16_f32 v41, v42, v43
	ds_read2_b32 v[42:43], v19 offset0:148 offset1:181
	s_waitcnt lgkmcnt(0)
	v_cvt_pk_bf16_f32 v42, v42, v43
	ds_read2_b32 v[44:45], v19 offset0:214 offset1:247
	s_waitcnt lgkmcnt(0)
	v_cvt_pk_bf16_f32 v43, v44, v45
	v_add_u32_e32 v44, 16, v10
	v_ashrrev_i32_e32 v45, 31, v44
	v_lshlrev_b64 v[44:45], 10, v[44:45]
	v_lshl_add_u64 v[44:45], v[8:9], 0, v[44:45]
	v_add_u32_e32 v10, 24, v10
	global_store_dwordx4 v[44:45], v[40:43], off
	ds_read2_b32 v[40:41], v19 offset0:24 offset1:57
	v_ashrrev_i32_e32 v11, 31, v10
	s_waitcnt lgkmcnt(0)
	v_cvt_pk_bf16_f32 v40, v40, v41
	ds_read2_b32 v[42:43], v19 offset0:90 offset1:123
	v_lshlrev_b64 v[10:11], 10, v[10:11]
	s_waitcnt lgkmcnt(0)
	v_cvt_pk_bf16_f32 v41, v42, v43
	ds_read2_b32 v[42:43], v19 offset0:156 offset1:189
	v_lshl_add_u64 v[8:9], v[8:9], 0, v[10:11]
	s_waitcnt lgkmcnt(0)
	v_cvt_pk_bf16_f32 v42, v42, v43
	ds_read2_b32 v[44:45], v19 offset0:222 offset1:255
	s_waitcnt lgkmcnt(0)
	v_cvt_pk_bf16_f32 v43, v44, v45
	global_store_dwordx4 v[8:9], v[40:43], off
	s_waitcnt lgkmcnt(0)
	s_andn2_b64 exec, exec, s[4:5]
	s_cbranch_execnz .LBB0_421

.LBB0_424:
	v_ashrrev_i32_e32 v6, 31, v40
	v_lshrrev_b32_e32 v6, 27, v6
	v_add_u32_e32 v6, v40, v6
	v_ashrrev_i32_e32 v6, 5, v6
	v_lshlrev_b32_e32 v8, 6, v6
	v_lshlrev_b32_e32 v6, 10, v6
	v_sub_u32_e32 v6, v24, v6
	v_or_b32_e32 v42, v8, v12
	v_ashrrev_i32_e32 v7, 31, v6
	v_ashrrev_i32_e32 v43, 31, v42
	v_lshl_add_u64 v[10:11], v[6:7], 2, v[2:3]
	v_lshlrev_b64 v[42:43], 12, v[42:43]
	v_or_b32_e32 v46, v8, v13
	v_lshl_add_u64 v[42:43], v[10:11], 0, v[42:43]
	v_ashrrev_i32_e32 v47, 31, v46
	global_load_dwordx4 v[42:45], v[42:43], off
	v_lshlrev_b64 v[46:47], 12, v[46:47]
	v_lshl_add_u64 v[46:47], v[10:11], 0, v[46:47]
	global_load_dwordx4 v[46:49], v[46:47], off
	v_add_u32_e32 v6, v6, v12
	v_ashrrev_i32_e32 v9, 31, v8
	v_ashrrev_i32_e32 v7, 31, v6
	v_add_u32_e32 v40, s8, v40
	s_movk_i32 s0, 0x7f
	v_cmp_lt_i32_e64 s[0:1], s0, v40
	v_add_u32_e32 v24, s9, v24
	s_or_b64 s[6:7], s[0:1], s[6:7]
	v_or_b32_e32 v226, v8, v14
	v_ashrrev_i32_e32 v227, 31, v226
	v_lshlrev_b64 v[226:227], 12, v[226:227]
	v_or_b32_e32 v230, v8, v15
	v_lshl_add_u64 v[226:227], v[10:11], 0, v[226:227]
	v_ashrrev_i32_e32 v231, 31, v230
	global_load_dwordx4 v[226:229], v[226:227], off
	v_lshlrev_b64 v[230:231], 12, v[230:231]
	v_lshl_add_u64 v[230:231], v[10:11], 0, v[230:231]
	global_load_dwordx4 v[230:233], v[230:231], off
	v_or_b32_e32 v234, v8, v16
	v_ashrrev_i32_e32 v235, 31, v234
	v_lshlrev_b64 v[234:235], 12, v[234:235]
	v_or_b32_e32 v238, v8, v17
	v_lshl_add_u64 v[234:235], v[10:11], 0, v[234:235]
	v_ashrrev_i32_e32 v239, 31, v238
	global_load_dwordx4 v[234:237], v[234:235], off
	v_lshlrev_b64 v[238:239], 12, v[238:239]
	v_lshl_add_u64 v[238:239], v[10:11], 0, v[238:239]
	global_load_dwordx4 v[238:241], v[238:239], off
	v_or_b32_e32 v242, v8, v18
	v_ashrrev_i32_e32 v243, 31, v242
	v_lshlrev_b64 v[242:243], 12, v[242:243]
	v_or_b32_e32 v246, v8, v19
	v_lshl_add_u64 v[242:243], v[10:11], 0, v[242:243]
	v_ashrrev_i32_e32 v247, 31, v246
	global_load_dwordx4 v[242:245], v[242:243], off
	v_lshlrev_b64 v[246:247], 12, v[246:247]
	v_lshl_add_u64 v[10:11], v[10:11], 0, v[246:247]
	global_load_dwordx4 v[246:249], v[10:11], off
	v_lshl_add_u64 v[8:9], v[8:9], 1, v[4:5]
	s_waitcnt vmcnt(7)
	ds_write2_b32 v25, v42, v43 offset1:1
	ds_write2_b32 v25, v44, v45 offset0:2 offset1:3
	s_waitcnt vmcnt(6)
	ds_write2_b32 v26, v46, v47 offset1:1
	ds_write2_b32 v27, v48, v49 offset1:1
	s_waitcnt vmcnt(5)
	ds_write2_b32 v28, v226, v227 offset1:1
	ds_write2_b32 v29, v228, v229 offset1:1
	s_waitcnt vmcnt(4)
	ds_write2_b32 v30, v230, v231 offset1:1
	ds_write2_b32 v31, v232, v233 offset1:1
	s_waitcnt lgkmcnt(7)
	s_waitcnt vmcnt(3)
	ds_write2_b32 v32, v234, v235 offset1:1
	ds_write2_b32 v33, v236, v237 offset1:1
	s_waitcnt vmcnt(2)
	ds_write2_b32 v34, v238, v239 offset1:1
	ds_write2_b32 v35, v240, v241 offset1:1
	s_waitcnt vmcnt(1)
	ds_write2_b32 v36, v242, v243 offset1:1
	ds_write2_b32 v37, v244, v245 offset1:1
	s_waitcnt vmcnt(0)
	ds_write2_b32 v38, v246, v247 offset1:1
	ds_write2_b32 v39, v248, v249 offset1:1
	s_waitcnt lgkmcnt(0)
	ds_read2_b32 v[10:11], v23 offset1:33
	s_waitcnt lgkmcnt(0)
	v_cvt_pk_bf16_f32 v42, v10, v11
	ds_read2_b32 v[10:11], v23 offset0:66 offset1:99
	s_waitcnt lgkmcnt(0)
	v_cvt_pk_bf16_f32 v43, v10, v11
	ds_read2_b32 v[10:11], v23 offset0:132 offset1:165
	s_waitcnt lgkmcnt(0)
	v_cvt_pk_bf16_f32 v44, v10, v11
	ds_read2_b32 v[10:11], v23 offset0:198 offset1:231
	s_waitcnt lgkmcnt(0)
	v_cvt_pk_bf16_f32 v45, v10, v11
	v_lshlrev_b64 v[10:11], 9, v[6:7]
	v_lshl_add_u64 v[10:11], v[8:9], 0, v[10:11]
	global_store_dwordx4 v[10:11], v[42:45], off
	ds_read2_b32 v[10:11], v23 offset0:8 offset1:41
	s_waitcnt lgkmcnt(0)
	v_cvt_pk_bf16_f32 v42, v10, v11
	ds_read2_b32 v[10:11], v23 offset0:74 offset1:107
	s_waitcnt lgkmcnt(0)
	v_cvt_pk_bf16_f32 v43, v10, v11
	ds_read2_b32 v[10:11], v23 offset0:140 offset1:173
	s_waitcnt lgkmcnt(0)
	v_cvt_pk_bf16_f32 v44, v10, v11
	ds_read2_b32 v[10:11], v23 offset0:206 offset1:239
	s_waitcnt lgkmcnt(0)
	v_cvt_pk_bf16_f32 v45, v10, v11
	v_add_u32_e32 v10, 8, v6
	v_ashrrev_i32_e32 v11, 31, v10
	v_lshlrev_b64 v[10:11], 9, v[10:11]
	v_lshl_add_u64 v[10:11], v[8:9], 0, v[10:11]
	global_store_dwordx4 v[10:11], v[42:45], off
	ds_read2_b32 v[10:11], v23 offset0:16 offset1:49
	s_waitcnt lgkmcnt(0)
	v_cvt_pk_bf16_f32 v42, v10, v11
	ds_read2_b32 v[10:11], v23 offset0:82 offset1:115
	s_waitcnt lgkmcnt(0)
	v_cvt_pk_bf16_f32 v43, v10, v11
	ds_read2_b32 v[10:11], v23 offset0:148 offset1:181
	s_waitcnt lgkmcnt(0)
	v_cvt_pk_bf16_f32 v44, v10, v11
	ds_read2_b32 v[10:11], v23 offset0:214 offset1:247
	s_waitcnt lgkmcnt(0)
	v_cvt_pk_bf16_f32 v45, v10, v11
	v_add_u32_e32 v10, 16, v6
	v_ashrrev_i32_e32 v11, 31, v10
	v_lshlrev_b64 v[10:11], 9, v[10:11]
	v_lshl_add_u64 v[10:11], v[8:9], 0, v[10:11]
	v_add_u32_e32 v6, 24, v6
	global_store_dwordx4 v[10:11], v[42:45], off
	ds_read2_b32 v[10:11], v23 offset0:24 offset1:57
	v_ashrrev_i32_e32 v7, 31, v6
	s_waitcnt lgkmcnt(0)
	v_cvt_pk_bf16_f32 v42, v10, v11
	ds_read2_b32 v[10:11], v23 offset0:90 offset1:123
	v_lshlrev_b64 v[6:7], 9, v[6:7]
	s_waitcnt lgkmcnt(0)
	v_cvt_pk_bf16_f32 v43, v10, v11
	ds_read2_b32 v[10:11], v23 offset0:156 offset1:189
	v_lshl_add_u64 v[6:7], v[8:9], 0, v[6:7]
	s_waitcnt lgkmcnt(0)
	v_cvt_pk_bf16_f32 v44, v10, v11
	ds_read2_b32 v[10:11], v23 offset0:222 offset1:255
	s_waitcnt lgkmcnt(0)
	v_cvt_pk_bf16_f32 v45, v10, v11
	global_store_dwordx4 v[6:7], v[42:45], off
	s_waitcnt lgkmcnt(0)
	s_andn2_b64 exec, exec, s[6:7]
	s_cbranch_execnz .LBB0_424

.LBB0_427:
	v_ashrrev_i32_e32 v6, 31, v40
	v_lshrrev_b32_e32 v6, 27, v6
	v_add_u32_e32 v6, v40, v6
	v_ashrrev_i32_e32 v6, 5, v6
	v_lshlrev_b32_e32 v8, 6, v6
	v_lshlrev_b32_e32 v6, 10, v6
	v_sub_u32_e32 v6, v24, v6
	v_or_b32_e32 v42, v8, v12
	v_ashrrev_i32_e32 v7, 31, v6
	v_ashrrev_i32_e32 v43, 31, v42
	v_lshl_add_u64 v[10:11], v[6:7], 2, v[2:3]
	v_lshlrev_b64 v[42:43], 12, v[42:43]
	v_or_b32_e32 v46, v8, v13
	v_lshl_add_u64 v[42:43], v[10:11], 0, v[42:43]
	v_ashrrev_i32_e32 v47, 31, v46
	global_load_dwordx4 v[42:45], v[42:43], off
	v_lshlrev_b64 v[46:47], 12, v[46:47]
	v_lshl_add_u64 v[46:47], v[10:11], 0, v[46:47]
	global_load_dwordx4 v[46:49], v[46:47], off
	v_add_u32_e32 v6, v6, v12
	v_ashrrev_i32_e32 v9, 31, v8
	v_ashrrev_i32_e32 v7, 31, v6
	v_add_u32_e32 v40, s8, v40
	s_movk_i32 s0, 0x7f
	v_cmp_lt_i32_e64 s[0:1], s0, v40
	v_add_u32_e32 v24, s6, v24
	s_or_b64 s[4:5], s[0:1], s[4:5]
	v_or_b32_e32 v226, v8, v14
	v_ashrrev_i32_e32 v227, 31, v226
	v_lshlrev_b64 v[226:227], 12, v[226:227]
	v_or_b32_e32 v230, v8, v15
	v_lshl_add_u64 v[226:227], v[10:11], 0, v[226:227]
	v_ashrrev_i32_e32 v231, 31, v230
	global_load_dwordx4 v[226:229], v[226:227], off
	v_lshlrev_b64 v[230:231], 12, v[230:231]
	v_lshl_add_u64 v[230:231], v[10:11], 0, v[230:231]
	global_load_dwordx4 v[230:233], v[230:231], off
	v_or_b32_e32 v234, v8, v16
	v_ashrrev_i32_e32 v235, 31, v234
	v_lshlrev_b64 v[234:235], 12, v[234:235]
	v_or_b32_e32 v238, v8, v17
	v_lshl_add_u64 v[234:235], v[10:11], 0, v[234:235]
	v_ashrrev_i32_e32 v239, 31, v238
	global_load_dwordx4 v[234:237], v[234:235], off
	v_lshlrev_b64 v[238:239], 12, v[238:239]
	v_lshl_add_u64 v[238:239], v[10:11], 0, v[238:239]
	global_load_dwordx4 v[238:241], v[238:239], off
	v_or_b32_e32 v242, v8, v18
	v_ashrrev_i32_e32 v243, 31, v242
	v_lshlrev_b64 v[242:243], 12, v[242:243]
	v_or_b32_e32 v246, v8, v19
	v_lshl_add_u64 v[242:243], v[10:11], 0, v[242:243]
	v_ashrrev_i32_e32 v247, 31, v246
	global_load_dwordx4 v[242:245], v[242:243], off
	v_lshlrev_b64 v[246:247], 12, v[246:247]
	v_lshl_add_u64 v[10:11], v[10:11], 0, v[246:247]
	global_load_dwordx4 v[246:249], v[10:11], off
	v_lshl_add_u64 v[8:9], v[8:9], 1, v[4:5]
	s_waitcnt vmcnt(7)
	ds_write2_b32 v25, v42, v43 offset1:1
	ds_write2_b32 v25, v44, v45 offset0:2 offset1:3
	s_waitcnt vmcnt(6)
	ds_write2_b32 v26, v46, v47 offset1:1
	ds_write2_b32 v27, v48, v49 offset1:1
	s_waitcnt vmcnt(5)
	ds_write2_b32 v28, v226, v227 offset1:1
	ds_write2_b32 v29, v228, v229 offset1:1
	s_waitcnt vmcnt(4)
	ds_write2_b32 v30, v230, v231 offset1:1
	ds_write2_b32 v31, v232, v233 offset1:1
	s_waitcnt lgkmcnt(7)
	s_waitcnt vmcnt(3)
	ds_write2_b32 v32, v234, v235 offset1:1
	ds_write2_b32 v33, v236, v237 offset1:1
	s_waitcnt vmcnt(2)
	ds_write2_b32 v34, v238, v239 offset1:1
	ds_write2_b32 v35, v240, v241 offset1:1
	s_waitcnt vmcnt(1)
	ds_write2_b32 v36, v242, v243 offset1:1
	ds_write2_b32 v37, v244, v245 offset1:1
	s_waitcnt vmcnt(0)
	ds_write2_b32 v38, v246, v247 offset1:1
	ds_write2_b32 v39, v248, v249 offset1:1
	s_waitcnt lgkmcnt(0)
	ds_read2_b32 v[10:11], v23 offset1:33
	s_waitcnt lgkmcnt(0)
	v_cvt_pk_bf16_f32 v42, v10, v11
	ds_read2_b32 v[10:11], v23 offset0:66 offset1:99
	s_waitcnt lgkmcnt(0)
	v_cvt_pk_bf16_f32 v43, v10, v11
	ds_read2_b32 v[10:11], v23 offset0:132 offset1:165
	s_waitcnt lgkmcnt(0)
	v_cvt_pk_bf16_f32 v44, v10, v11
	ds_read2_b32 v[10:11], v23 offset0:198 offset1:231
	s_waitcnt lgkmcnt(0)
	v_cvt_pk_bf16_f32 v45, v10, v11
	v_lshlrev_b64 v[10:11], 9, v[6:7]
	v_lshl_add_u64 v[10:11], v[8:9], 0, v[10:11]
	global_store_dwordx4 v[10:11], v[42:45], off
	ds_read2_b32 v[10:11], v23 offset0:8 offset1:41
	s_waitcnt lgkmcnt(0)
	v_cvt_pk_bf16_f32 v42, v10, v11
	ds_read2_b32 v[10:11], v23 offset0:74 offset1:107
	s_waitcnt lgkmcnt(0)
	v_cvt_pk_bf16_f32 v43, v10, v11
	ds_read2_b32 v[10:11], v23 offset0:140 offset1:173
	s_waitcnt lgkmcnt(0)
	v_cvt_pk_bf16_f32 v44, v10, v11
	ds_read2_b32 v[10:11], v23 offset0:206 offset1:239
	s_waitcnt lgkmcnt(0)
	v_cvt_pk_bf16_f32 v45, v10, v11
	v_add_u32_e32 v10, 8, v6
	v_ashrrev_i32_e32 v11, 31, v10
	v_lshlrev_b64 v[10:11], 9, v[10:11]
	v_lshl_add_u64 v[10:11], v[8:9], 0, v[10:11]
	global_store_dwordx4 v[10:11], v[42:45], off
	ds_read2_b32 v[10:11], v23 offset0:16 offset1:49
	s_waitcnt lgkmcnt(0)
	v_cvt_pk_bf16_f32 v42, v10, v11
	ds_read2_b32 v[10:11], v23 offset0:82 offset1:115
	s_waitcnt lgkmcnt(0)
	v_cvt_pk_bf16_f32 v43, v10, v11
	ds_read2_b32 v[10:11], v23 offset0:148 offset1:181
	s_waitcnt lgkmcnt(0)
	v_cvt_pk_bf16_f32 v44, v10, v11
	ds_read2_b32 v[10:11], v23 offset0:214 offset1:247
	s_waitcnt lgkmcnt(0)
	v_cvt_pk_bf16_f32 v45, v10, v11
	v_add_u32_e32 v10, 16, v6
	v_ashrrev_i32_e32 v11, 31, v10
	v_lshlrev_b64 v[10:11], 9, v[10:11]
	v_lshl_add_u64 v[10:11], v[8:9], 0, v[10:11]
	v_add_u32_e32 v6, 24, v6
	global_store_dwordx4 v[10:11], v[42:45], off
	ds_read2_b32 v[10:11], v23 offset0:24 offset1:57
	v_ashrrev_i32_e32 v7, 31, v6
	s_waitcnt lgkmcnt(0)
	v_cvt_pk_bf16_f32 v42, v10, v11
	ds_read2_b32 v[10:11], v23 offset0:90 offset1:123
	v_lshlrev_b64 v[6:7], 9, v[6:7]
	s_waitcnt lgkmcnt(0)
	v_cvt_pk_bf16_f32 v43, v10, v11
	ds_read2_b32 v[10:11], v23 offset0:156 offset1:189
	v_lshl_add_u64 v[6:7], v[8:9], 0, v[6:7]
	s_waitcnt lgkmcnt(0)
	v_cvt_pk_bf16_f32 v44, v10, v11
	ds_read2_b32 v[10:11], v23 offset0:222 offset1:255
	s_waitcnt lgkmcnt(0)
	v_cvt_pk_bf16_f32 v45, v10, v11
	global_store_dwordx4 v[6:7], v[42:45], off
	s_waitcnt lgkmcnt(0)
	s_andn2_b64 exec, exec, s[4:5]
	s_cbranch_execnz .LBB0_427

.LBB0_430:
	v_ashrrev_i32_e32 v6, 31, v20
	v_lshrrev_b32_e32 v6, 27, v6
	v_add_u32_e32 v6, v20, v6
	v_ashrrev_i32_e32 v6, 5, v6
	v_lshlrev_b32_e32 v8, 6, v6
	v_lshlrev_b32_e32 v6, 10, v6
	v_sub_u32_e32 v6, v21, v6
	v_or_b32_e32 v38, v8, v12
	v_ashrrev_i32_e32 v7, 31, v6
	v_ashrrev_i32_e32 v39, 31, v38
	v_lshl_add_u64 v[10:11], v[6:7], 2, v[2:3]
	v_lshlrev_b64 v[38:39], 12, v[38:39]
	v_or_b32_e32 v42, v8, v13
	v_lshl_add_u64 v[38:39], v[10:11], 0, v[38:39]
	v_ashrrev_i32_e32 v43, 31, v42
	global_load_dwordx4 v[38:41], v[38:39], off
	v_lshlrev_b64 v[42:43], 12, v[42:43]
	v_lshl_add_u64 v[42:43], v[10:11], 0, v[42:43]
	global_load_dwordx4 v[42:45], v[42:43], off
	v_add_u32_e32 v6, v6, v12
	v_ashrrev_i32_e32 v9, 31, v8
	v_ashrrev_i32_e32 v7, 31, v6
	v_add_u32_e32 v20, s8, v20
	v_cmp_lt_i32_e32 vcc, s5, v20
	v_add_u32_e32 v21, s4, v21
	s_or_b64 s[2:3], vcc, s[2:3]
	v_or_b32_e32 v226, v8, v14
	v_ashrrev_i32_e32 v227, 31, v226
	v_lshlrev_b64 v[226:227], 12, v[226:227]
	v_or_b32_e32 v230, v8, v15
	v_lshl_add_u64 v[226:227], v[10:11], 0, v[226:227]
	v_ashrrev_i32_e32 v231, 31, v230
	global_load_dwordx4 v[226:229], v[226:227], off
	v_lshlrev_b64 v[230:231], 12, v[230:231]
	v_lshl_add_u64 v[230:231], v[10:11], 0, v[230:231]
	global_load_dwordx4 v[230:233], v[230:231], off
	v_or_b32_e32 v234, v8, v16
	v_ashrrev_i32_e32 v235, 31, v234
	v_lshlrev_b64 v[234:235], 12, v[234:235]
	v_or_b32_e32 v238, v8, v17
	v_lshl_add_u64 v[234:235], v[10:11], 0, v[234:235]
	v_ashrrev_i32_e32 v239, 31, v238
	global_load_dwordx4 v[234:237], v[234:235], off
	v_lshlrev_b64 v[238:239], 12, v[238:239]
	v_lshl_add_u64 v[238:239], v[10:11], 0, v[238:239]
	global_load_dwordx4 v[238:241], v[238:239], off
	v_or_b32_e32 v242, v8, v18
	v_ashrrev_i32_e32 v243, 31, v242
	v_lshlrev_b64 v[242:243], 12, v[242:243]
	v_or_b32_e32 v246, v8, v19
	v_lshl_add_u64 v[242:243], v[10:11], 0, v[242:243]
	v_ashrrev_i32_e32 v247, 31, v246
	global_load_dwordx4 v[242:245], v[242:243], off
	v_lshlrev_b64 v[246:247], 12, v[246:247]
	v_lshl_add_u64 v[10:11], v[10:11], 0, v[246:247]
	global_load_dwordx4 v[246:249], v[10:11], off
	v_lshl_add_u64 v[8:9], v[8:9], 1, v[4:5]
	s_waitcnt vmcnt(7)
	ds_write2_b32 v23, v38, v39 offset1:1
	ds_write2_b32 v23, v40, v41 offset0:2 offset1:3
	s_waitcnt vmcnt(6)
	ds_write2_b32 v24, v42, v43 offset1:1
	ds_write2_b32 v25, v44, v45 offset1:1
	s_waitcnt vmcnt(5)
	ds_write2_b32 v26, v226, v227 offset1:1
	ds_write2_b32 v27, v228, v229 offset1:1
	s_waitcnt vmcnt(4)
	ds_write2_b32 v28, v230, v231 offset1:1
	ds_write2_b32 v29, v232, v233 offset1:1
	s_waitcnt lgkmcnt(7)
	s_waitcnt vmcnt(3)
	ds_write2_b32 v30, v234, v235 offset1:1
	ds_write2_b32 v31, v236, v237 offset1:1
	s_waitcnt vmcnt(2)
	ds_write2_b32 v32, v238, v239 offset1:1
	ds_write2_b32 v33, v240, v241 offset1:1
	s_waitcnt vmcnt(1)
	ds_write2_b32 v34, v242, v243 offset1:1
	ds_write2_b32 v35, v244, v245 offset1:1
	s_waitcnt vmcnt(0)
	ds_write2_b32 v36, v246, v247 offset1:1
	ds_write2_b32 v37, v248, v249 offset1:1
	s_waitcnt lgkmcnt(0)
	ds_read2_b32 v[10:11], v22 offset1:33
	s_waitcnt lgkmcnt(0)
	v_cvt_pk_bf16_f32 v38, v10, v11
	ds_read2_b32 v[10:11], v22 offset0:66 offset1:99
	s_waitcnt lgkmcnt(0)
	v_cvt_pk_bf16_f32 v39, v10, v11
	ds_read2_b32 v[10:11], v22 offset0:132 offset1:165
	s_waitcnt lgkmcnt(0)
	v_cvt_pk_bf16_f32 v40, v10, v11
	ds_read2_b32 v[10:11], v22 offset0:198 offset1:231
	s_waitcnt lgkmcnt(0)
	v_cvt_pk_bf16_f32 v41, v10, v11
	v_lshlrev_b64 v[10:11], 11, v[6:7]
	v_lshl_add_u64 v[10:11], v[8:9], 0, v[10:11]
	global_store_dwordx4 v[10:11], v[38:41], off
	ds_read2_b32 v[10:11], v22 offset0:8 offset1:41
	s_waitcnt lgkmcnt(0)
	v_cvt_pk_bf16_f32 v38, v10, v11
	ds_read2_b32 v[10:11], v22 offset0:74 offset1:107
	s_waitcnt lgkmcnt(0)
	v_cvt_pk_bf16_f32 v39, v10, v11
	ds_read2_b32 v[10:11], v22 offset0:140 offset1:173
	s_waitcnt lgkmcnt(0)
	v_cvt_pk_bf16_f32 v40, v10, v11
	ds_read2_b32 v[10:11], v22 offset0:206 offset1:239
	s_waitcnt lgkmcnt(0)
	v_cvt_pk_bf16_f32 v41, v10, v11
	v_add_u32_e32 v10, 8, v6
	v_ashrrev_i32_e32 v11, 31, v10
	v_lshlrev_b64 v[10:11], 11, v[10:11]
	v_lshl_add_u64 v[10:11], v[8:9], 0, v[10:11]
	global_store_dwordx4 v[10:11], v[38:41], off
	ds_read2_b32 v[10:11], v22 offset0:16 offset1:49
	s_waitcnt lgkmcnt(0)
	v_cvt_pk_bf16_f32 v38, v10, v11
	ds_read2_b32 v[10:11], v22 offset0:82 offset1:115
	s_waitcnt lgkmcnt(0)
	v_cvt_pk_bf16_f32 v39, v10, v11
	ds_read2_b32 v[10:11], v22 offset0:148 offset1:181
	s_waitcnt lgkmcnt(0)
	v_cvt_pk_bf16_f32 v40, v10, v11
	ds_read2_b32 v[10:11], v22 offset0:214 offset1:247
	s_waitcnt lgkmcnt(0)
	v_cvt_pk_bf16_f32 v41, v10, v11
	v_add_u32_e32 v10, 16, v6
	v_ashrrev_i32_e32 v11, 31, v10
	v_lshlrev_b64 v[10:11], 11, v[10:11]
	v_lshl_add_u64 v[10:11], v[8:9], 0, v[10:11]
	v_add_u32_e32 v6, 24, v6
	global_store_dwordx4 v[10:11], v[38:41], off
	ds_read2_b32 v[10:11], v22 offset0:24 offset1:57
	v_ashrrev_i32_e32 v7, 31, v6
	s_waitcnt lgkmcnt(0)
	v_cvt_pk_bf16_f32 v38, v10, v11
	ds_read2_b32 v[10:11], v22 offset0:90 offset1:123
	v_lshlrev_b64 v[6:7], 11, v[6:7]
	s_waitcnt lgkmcnt(0)
	v_cvt_pk_bf16_f32 v39, v10, v11
	ds_read2_b32 v[10:11], v22 offset0:156 offset1:189
	v_lshl_add_u64 v[6:7], v[8:9], 0, v[6:7]
	s_waitcnt lgkmcnt(0)
	v_cvt_pk_bf16_f32 v40, v10, v11
	ds_read2_b32 v[10:11], v22 offset0:222 offset1:255
	s_waitcnt lgkmcnt(0)
	v_cvt_pk_bf16_f32 v41, v10, v11
	global_store_dwordx4 v[6:7], v[38:41], off
	s_waitcnt lgkmcnt(0)
	s_andn2_b64 exec, exec, s[2:3]
	s_cbranch_execnz .LBB0_430

.LBB0_730:
.LBB0_731:
	v_lshl_or_b32 v144, s20, 8, v135
	v_lshl_add_u32 v150, s18, 8, v134
	v_ashrrev_i32_e32 v145, 31, v144
	v_lshlrev_b64 v[144:145], 2, v[144:145]
	v_ashrrev_i32_e32 v151, 31, v150
	v_lshl_add_u64 v[146:147], s[4:5], 0, v[144:145]
	v_lshlrev_b64 v[148:149], 12, v[150:151]
	v_or_b32_e32 v172, 16, v150
	v_lshl_add_u64 v[168:169], v[146:147], 0, v[148:149]
	v_ashrrev_i32_e32 v173, 31, v172
	v_mov_b64_e32 v[224:225], v[168:169]
	global_load_dwordx4 v[156:159], v[168:169], off
	global_load_dwordx4 v[160:163], v[168:169], off offset:64
	global_load_dwordx4 v[164:167], v[168:169], off offset:512
	s_nop 0
	global_load_dwordx4 v[168:171], v[168:169], off offset:576
	v_lshlrev_b64 v[188:189], 12, v[172:173]
	v_lshl_add_u64 v[184:185], v[146:147], 0, v[188:189]
	global_load_dwordx4 v[172:175], v[184:185], off
	global_load_dwordx4 v[176:179], v[184:185], off offset:64
	global_load_dwordx4 v[180:183], v[184:185], off offset:512
	s_nop 0
	global_load_dwordx4 v[184:187], v[184:185], off offset:576
	v_add_co_u32_e32 v226, vcc, 0x20000, v224
	s_nop 1
	v_addc_co_u32_e32 v227, vcc, 0, v225, vcc
	v_add_co_u32_e32 v228, vcc, 0x30000, v224
	s_nop 1
	v_addc_co_u32_e32 v229, vcc, 0, v225, vcc
	global_load_dwordx4 v[192:195], v[226:227], off
	global_load_dwordx4 v[196:199], v[226:227], off offset:64
	global_load_dwordx4 v[200:203], v[226:227], off offset:512
	global_load_dwordx4 v[204:207], v[226:227], off offset:576
	global_load_dwordx4 v[208:211], v[228:229], off
	global_load_dwordx4 v[212:215], v[228:229], off offset:64
	global_load_dwordx4 v[216:219], v[228:229], off offset:512
	global_load_dwordx4 v[220:223], v[228:229], off offset:576
	v_lshl_add_u64 v[190:191], s[88:89], 0, v[148:149]
	v_lshl_add_u64 v[190:191], v[190:191], 0, v[144:145]
	s_mov_b64 s[18:19], 0x80000
	s_waitcnt vmcnt(8)
	v_pk_add_f32 v[128:129], v[128:129], v[158:159]
	v_pk_add_f32 v[126:127], v[126:127], v[156:157]
	v_pk_add_f32 v[112:113], v[112:113], v[166:167]
	v_pk_add_f32 v[108:109], v[108:109], v[170:171]
	v_pk_add_f32 v[106:107], v[106:107], v[168:169]
	v_pk_add_f32 v[110:111], v[110:111], v[164:165]
	global_store_dwordx4 v[190:191], v[106:109], off offset:576
	global_store_dwordx4 v[190:191], v[110:113], off offset:512
	v_pk_add_f32 v[100:101], v[100:101], v[186:187]
	v_lshl_add_u64 v[106:107], s[88:89], 0, v[188:189]
	v_lshl_add_u64 v[110:111], v[106:107], 0, v[144:145]
	v_pk_add_f32 v[98:99], v[98:99], v[184:185]
	global_store_dwordx4 v[110:111], v[98:101], off offset:576
	v_pk_add_f32 v[108:109], v[120:121], v[174:175]
	v_pk_add_f32 v[106:107], v[118:119], v[172:173]
	v_or_b32_e32 v98, 32, v150
	v_ashrrev_i32_e32 v99, 31, v98
	v_pk_add_f32 v[124:125], v[124:125], v[162:163]
	v_pk_add_f32 v[122:123], v[122:123], v[160:161]
	global_store_dwordx4 v[110:111], v[106:109], off
	v_pk_add_f32 v[104:105], v[104:105], v[182:183]
	v_pk_add_f32 v[102:103], v[102:103], v[180:181]
	v_pk_add_f32 v[108:109], v[116:117], v[178:179]
	v_pk_add_f32 v[106:107], v[114:115], v[176:177]
	v_lshlrev_b64 v[156:157], 12, v[98:99]
	global_store_dwordx4 v[190:191], v[126:129], off
	global_store_dwordx4 v[190:191], v[122:125], off offset:64
	global_store_dwordx4 v[110:111], v[106:109], off offset:64
	global_store_dwordx4 v[110:111], v[102:105], off offset:512
	v_lshl_add_u64 v[110:111], v[146:147], 0, v[156:157]
	v_or_b32_e32 v114, 48, v150
	s_nop 0
	v_ashrrev_i32_e32 v115, 31, v114
	v_lshlrev_b64 v[150:151], 12, v[114:115]
	v_lshl_add_u64 v[126:127], v[146:147], 0, v[150:151]
	s_nop 0
	s_nop 1
	s_waitcnt vmcnt(8)
	v_mov_b64_e32 v[98:99], v[192:193]
	v_mov_b64_e32 v[100:101], v[194:195]
	v_mov_b64_e32 v[102:103], v[196:197]
	v_mov_b64_e32 v[104:105], v[198:199]
	v_mov_b64_e32 v[106:107], v[200:201]
	v_mov_b64_e32 v[108:109], v[202:203]
	v_mov_b64_e32 v[110:111], v[204:205]
	v_mov_b64_e32 v[112:113], v[206:207]
	v_mov_b64_e32 v[114:115], v[208:209]
	v_mov_b64_e32 v[116:117], v[210:211]
	v_mov_b64_e32 v[118:119], v[212:213]
	v_mov_b64_e32 v[120:121], v[214:215]
	v_mov_b64_e32 v[122:123], v[216:217]
	v_mov_b64_e32 v[124:125], v[218:219]
	v_mov_b64_e32 v[126:127], v[220:221]
	v_mov_b64_e32 v[128:129], v[222:223]
	v_add_co_u32_e32 v226, vcc, 0x80000, v224
	s_nop 1
	v_addc_co_u32_e32 v227, vcc, 0, v225, vcc
	v_add_co_u32_e32 v228, vcc, 0x90000, v224
	s_nop 1
	v_addc_co_u32_e32 v229, vcc, 0, v225, vcc
	global_load_dwordx4 v[192:195], v[226:227], off
	global_load_dwordx4 v[196:199], v[226:227], off offset:64
	global_load_dwordx4 v[200:203], v[226:227], off offset:512
	global_load_dwordx4 v[204:207], v[226:227], off offset:576
	global_load_dwordx4 v[208:211], v[228:229], off
	global_load_dwordx4 v[212:215], v[228:229], off offset:64
	global_load_dwordx4 v[216:219], v[228:229], off offset:512
	global_load_dwordx4 v[220:223], v[228:229], off offset:576
	v_lshl_add_u64 v[156:157], s[88:89], 0, v[156:157]
	v_lshl_add_u64 v[156:157], v[156:157], 0, v[144:145]
	v_pk_add_f32 v[96:97], v[96:97], v[100:101]
	v_pk_add_f32 v[94:95], v[94:95], v[98:99]
	v_pk_add_f32 v[80:81], v[80:81], v[108:109]
	v_pk_add_f32 v[76:77], v[76:77], v[112:113]
	v_pk_add_f32 v[74:75], v[74:75], v[110:111]
	v_pk_add_f32 v[78:79], v[78:79], v[106:107]
	global_store_dwordx4 v[156:157], v[74:77], off offset:576
	global_store_dwordx4 v[156:157], v[78:81], off offset:512
	v_pk_add_f32 v[92:93], v[92:93], v[104:105]
	v_lshl_add_u64 v[74:75], s[88:89], 0, v[150:151]
	v_lshl_add_u64 v[78:79], v[74:75], 0, v[144:145]
	v_pk_add_f32 v[76:77], v[88:89], v[116:117]
	v_pk_add_f32 v[74:75], v[86:87], v[114:115]
	v_pk_add_f32 v[90:91], v[90:91], v[102:103]
	global_store_dwordx4 v[78:79], v[74:77], off
	v_pk_add_f32 v[72:73], v[72:73], v[124:125]
	v_pk_add_f32 v[70:71], v[70:71], v[122:123]
	v_pk_add_f32 v[76:77], v[84:85], v[120:121]
	v_pk_add_f32 v[74:75], v[82:83], v[118:119]
	v_pk_add_f32 v[68:69], v[68:69], v[128:129]
	v_pk_add_f32 v[66:67], v[66:67], v[126:127]
	v_lshl_add_u64 v[98:99], v[148:149], 0, s[18:19]
	global_store_dwordx4 v[156:157], v[94:97], off
	global_store_dwordx4 v[156:157], v[90:93], off offset:64
	global_store_dwordx4 v[78:79], v[74:77], off offset:64
	global_store_dwordx4 v[78:79], v[70:73], off offset:512
	global_store_dwordx4 v[78:79], v[66:69], off offset:576
	v_lshl_add_u64 v[78:79], v[146:147], 0, v[98:99]
	s_nop 0
	s_mov_b64 s[18:19], 0x90000
	v_lshl_add_u64 v[100:101], v[148:149], 0, s[18:19]
	v_lshl_add_u64 v[94:95], v[146:147], 0, v[100:101]
	s_nop 0
	s_nop 1
	s_waitcnt vmcnt(8)
	v_mov_b64_e32 v[66:67], v[192:193]
	v_mov_b64_e32 v[68:69], v[194:195]
	v_mov_b64_e32 v[70:71], v[196:197]
	v_mov_b64_e32 v[72:73], v[198:199]
	v_mov_b64_e32 v[74:75], v[200:201]
	v_mov_b64_e32 v[76:77], v[202:203]
	v_mov_b64_e32 v[78:79], v[204:205]
	v_mov_b64_e32 v[80:81], v[206:207]
	v_mov_b64_e32 v[82:83], v[208:209]
	v_mov_b64_e32 v[84:85], v[210:211]
	v_mov_b64_e32 v[86:87], v[212:213]
	v_mov_b64_e32 v[88:89], v[214:215]
	v_mov_b64_e32 v[90:91], v[216:217]
	v_mov_b64_e32 v[92:93], v[218:219]
	v_mov_b64_e32 v[94:95], v[220:221]
	v_mov_b64_e32 v[96:97], v[222:223]
	v_add_co_u32_e32 v226, vcc, 0xa0000, v224
	s_nop 1
	v_addc_co_u32_e32 v227, vcc, 0, v225, vcc
	v_add_co_u32_e32 v228, vcc, 0xb0000, v224
	s_nop 1
	v_addc_co_u32_e32 v229, vcc, 0, v225, vcc
	global_load_dwordx4 v[192:195], v[226:227], off
	global_load_dwordx4 v[196:199], v[226:227], off offset:64
	global_load_dwordx4 v[200:203], v[226:227], off offset:512
	global_load_dwordx4 v[204:207], v[226:227], off offset:576
	global_load_dwordx4 v[208:211], v[228:229], off
	global_load_dwordx4 v[212:215], v[228:229], off offset:64
	global_load_dwordx4 v[216:219], v[228:229], off offset:512
	global_load_dwordx4 v[220:223], v[228:229], off offset:576
	v_lshl_add_u64 v[98:99], s[88:89], 0, v[98:99]
	v_lshl_add_u64 v[98:99], v[98:99], 0, v[144:145]
	s_mov_b64 s[18:19], 0xa0000
	v_pk_add_f32 v[64:65], v[64:65], v[68:69]
	v_pk_add_f32 v[62:63], v[62:63], v[66:67]
	v_pk_add_f32 v[48:49], v[48:49], v[76:77]
	v_pk_add_f32 v[44:45], v[44:45], v[80:81]
	v_pk_add_f32 v[42:43], v[42:43], v[78:79]
	v_pk_add_f32 v[46:47], v[46:47], v[74:75]
	global_store_dwordx4 v[98:99], v[42:45], off offset:576
	global_store_dwordx4 v[98:99], v[46:49], off offset:512
	v_pk_add_f32 v[60:61], v[60:61], v[72:73]
	v_lshl_add_u64 v[42:43], s[88:89], 0, v[100:101]
	v_lshl_add_u64 v[46:47], v[42:43], 0, v[144:145]
	v_pk_add_f32 v[44:45], v[56:57], v[84:85]
	v_pk_add_f32 v[42:43], v[54:55], v[82:83]
	v_pk_add_f32 v[58:59], v[58:59], v[70:71]
	global_store_dwordx4 v[46:47], v[42:45], off
	v_pk_add_f32 v[40:41], v[40:41], v[92:93]
	v_pk_add_f32 v[38:39], v[38:39], v[90:91]
	v_pk_add_f32 v[44:45], v[52:53], v[88:89]
	v_pk_add_f32 v[42:43], v[50:51], v[86:87]
	v_pk_add_f32 v[36:37], v[36:37], v[96:97]
	v_pk_add_f32 v[34:35], v[34:35], v[94:95]
	v_lshl_add_u64 v[66:67], v[148:149], 0, s[18:19]
	global_store_dwordx4 v[98:99], v[62:65], off
	global_store_dwordx4 v[98:99], v[58:61], off offset:64
	global_store_dwordx4 v[46:47], v[42:45], off offset:64
	global_store_dwordx4 v[46:47], v[38:41], off offset:512
	global_store_dwordx4 v[46:47], v[34:37], off offset:576
	v_lshl_add_u64 v[46:47], v[146:147], 0, v[66:67]
	s_mov_b64 s[18:19], 0xb0000
	s_nop 0
	v_lshl_add_u64 v[68:69], v[148:149], 0, s[18:19]
	v_lshl_add_u64 v[62:63], v[146:147], 0, v[68:69]
	s_nop 0
	s_nop 1
	s_waitcnt vmcnt(8)
	v_mov_b64_e32 v[34:35], v[192:193]
	v_mov_b64_e32 v[36:37], v[194:195]
	v_mov_b64_e32 v[38:39], v[196:197]
	v_mov_b64_e32 v[40:41], v[198:199]
	v_mov_b64_e32 v[42:43], v[200:201]
	v_mov_b64_e32 v[44:45], v[202:203]
	v_mov_b64_e32 v[46:47], v[204:205]
	v_mov_b64_e32 v[48:49], v[206:207]
	v_mov_b64_e32 v[50:51], v[208:209]
	v_mov_b64_e32 v[52:53], v[210:211]
	v_mov_b64_e32 v[54:55], v[212:213]
	v_mov_b64_e32 v[56:57], v[214:215]
	v_mov_b64_e32 v[58:59], v[216:217]
	v_mov_b64_e32 v[60:61], v[218:219]
	v_mov_b64_e32 v[62:63], v[220:221]
	v_mov_b64_e32 v[64:65], v[222:223]
	v_lshl_add_u64 v[66:67], s[88:89], 0, v[66:67]
	v_lshl_add_u64 v[66:67], v[66:67], 0, v[144:145]
	v_pk_add_f32 v[32:33], v[32:33], v[36:37]
	v_pk_add_f32 v[30:31], v[30:31], v[34:35]
	v_pk_add_f32 v[28:29], v[28:29], v[40:41]
	v_pk_add_f32 v[20:21], v[20:21], v[48:49]
	v_pk_add_f32 v[18:19], v[18:19], v[46:47]
	global_store_dwordx4 v[66:67], v[18:21], off offset:576
	v_pk_add_f32 v[26:27], v[26:27], v[38:39]
	v_pk_add_f32 v[24:25], v[24:25], v[44:45]
	v_lshl_add_u64 v[18:19], s[88:89], 0, v[68:69]
	v_pk_add_f32 v[22:23], v[22:23], v[42:43]
	v_lshl_add_u64 v[18:19], v[18:19], 0, v[144:145]
	v_pk_add_f32 v[16:17], v[16:17], v[52:53]
	v_pk_add_f32 v[14:15], v[14:15], v[50:51]
	v_pk_add_f32 v[12:13], v[12:13], v[56:57]
	v_pk_add_f32 v[10:11], v[10:11], v[54:55]
	v_pk_add_f32 v[8:9], v[8:9], v[60:61]
	v_pk_add_f32 v[6:7], v[6:7], v[58:59]
	v_pk_add_f32 v[4:5], v[4:5], v[64:65]
	v_pk_add_f32 v[2:3], v[2:3], v[62:63]
	global_store_dwordx4 v[66:67], v[30:33], off
	global_store_dwordx4 v[66:67], v[26:29], off offset:64
	global_store_dwordx4 v[66:67], v[22:25], off offset:512
	global_store_dwordx4 v[18:19], v[14:17], off
	global_store_dwordx4 v[18:19], v[10:13], off offset:64
	global_store_dwordx4 v[18:19], v[6:9], off offset:512
	global_store_dwordx4 v[18:19], v[2:5], off offset:576
	s_branch .LBB0_716

.LBB0_882:
	v_ashrrev_i32_e32 v6, 31, v40
	v_lshrrev_b32_e32 v6, 25, v6
	v_add_u32_e32 v6, v40, v6
	v_ashrrev_i32_e32 v6, 7, v6
	v_lshlrev_b32_e32 v8, 6, v6
	v_lshlrev_b32_e32 v6, 12, v6
	v_sub_u32_e32 v6, v24, v6
	v_or_b32_e32 v42, v8, v15
	v_ashrrev_i32_e32 v7, 31, v6
	v_ashrrev_i32_e32 v43, 31, v42
	v_lshl_add_u64 v[10:11], v[6:7], 2, v[2:3]
	v_lshlrev_b64 v[42:43], 14, v[42:43]
	v_or_b32_e32 v46, v8, v16
	v_lshl_add_u64 v[42:43], v[10:11], 0, v[42:43]
	v_ashrrev_i32_e32 v47, 31, v46
	global_load_dwordx4 v[42:45], v[42:43], off
	v_lshlrev_b64 v[46:47], 14, v[46:47]
	v_lshl_add_u64 v[46:47], v[10:11], 0, v[46:47]
	global_load_dwordx4 v[46:49], v[46:47], off
	v_add_u32_e32 v6, v6, v15
	v_ashrrev_i32_e32 v9, 31, v8
	v_ashrrev_i32_e32 v7, 31, v6
	v_add_u32_e32 v40, s4, v40
	s_movk_i32 s0, 0x7ff
	v_cmp_lt_i32_e64 s[0:1], s0, v40
	v_add_u32_e32 v24, s5, v24
	s_or_b64 s[6:7], s[0:1], s[6:7]
	v_or_b32_e32 v226, v8, v17
	v_ashrrev_i32_e32 v227, 31, v226
	v_lshlrev_b64 v[226:227], 14, v[226:227]
	v_or_b32_e32 v230, v8, v18
	v_lshl_add_u64 v[226:227], v[10:11], 0, v[226:227]
	v_ashrrev_i32_e32 v231, 31, v230
	global_load_dwordx4 v[226:229], v[226:227], off
	v_lshlrev_b64 v[230:231], 14, v[230:231]
	v_lshl_add_u64 v[230:231], v[10:11], 0, v[230:231]
	global_load_dwordx4 v[230:233], v[230:231], off
	v_or_b32_e32 v234, v8, v19
	v_ashrrev_i32_e32 v235, 31, v234
	v_lshlrev_b64 v[234:235], 14, v[234:235]
	v_or_b32_e32 v238, v8, v20
	v_lshl_add_u64 v[234:235], v[10:11], 0, v[234:235]
	v_ashrrev_i32_e32 v239, 31, v238
	global_load_dwordx4 v[234:237], v[234:235], off
	v_lshlrev_b64 v[238:239], 14, v[238:239]
	v_lshl_add_u64 v[238:239], v[10:11], 0, v[238:239]
	global_load_dwordx4 v[238:241], v[238:239], off
	v_or_b32_e32 v242, v8, v21
	v_ashrrev_i32_e32 v243, 31, v242
	v_lshlrev_b64 v[242:243], 14, v[242:243]
	v_or_b32_e32 v246, v8, v22
	v_lshl_add_u64 v[242:243], v[10:11], 0, v[242:243]
	v_ashrrev_i32_e32 v247, 31, v246
	global_load_dwordx4 v[242:245], v[242:243], off
	v_lshlrev_b64 v[246:247], 14, v[246:247]
	v_lshl_add_u64 v[10:11], v[10:11], 0, v[246:247]
	global_load_dwordx4 v[246:249], v[10:11], off
	v_lshl_add_u64 v[8:9], v[8:9], 1, v[4:5]
	s_waitcnt vmcnt(7)
	ds_write2_b32 v25, v42, v43 offset1:1
	ds_write2_b32 v25, v44, v45 offset0:2 offset1:3
	s_waitcnt vmcnt(6)
	ds_write2_b32 v26, v46, v47 offset1:1
	ds_write2_b32 v27, v48, v49 offset1:1
	s_waitcnt vmcnt(5)
	ds_write2_b32 v28, v226, v227 offset1:1
	ds_write2_b32 v29, v228, v229 offset1:1
	s_waitcnt vmcnt(4)
	ds_write2_b32 v30, v230, v231 offset1:1
	ds_write2_b32 v31, v232, v233 offset1:1
	s_waitcnt lgkmcnt(7)
	s_waitcnt vmcnt(3)
	ds_write2_b32 v32, v234, v235 offset1:1
	ds_write2_b32 v33, v236, v237 offset1:1
	s_waitcnt vmcnt(2)
	ds_write2_b32 v34, v238, v239 offset1:1
	ds_write2_b32 v35, v240, v241 offset1:1
	s_waitcnt vmcnt(1)
	ds_write2_b32 v36, v242, v243 offset1:1
	ds_write2_b32 v37, v244, v245 offset1:1
	s_waitcnt vmcnt(0)
	ds_write2_b32 v38, v246, v247 offset1:1
	ds_write2_b32 v39, v248, v249 offset1:1
	s_waitcnt lgkmcnt(0)
	ds_read2_b32 v[10:11], v23 offset1:33
	s_waitcnt lgkmcnt(0)
	v_cvt_pk_bf16_f32 v42, v10, v11
	ds_read2_b32 v[10:11], v23 offset0:66 offset1:99
	s_waitcnt lgkmcnt(0)
	v_cvt_pk_bf16_f32 v43, v10, v11
	ds_read2_b32 v[10:11], v23 offset0:132 offset1:165
	s_waitcnt lgkmcnt(0)
	v_cvt_pk_bf16_f32 v44, v10, v11
	ds_read2_b32 v[10:11], v23 offset0:198 offset1:231
	s_waitcnt lgkmcnt(0)
	v_cvt_pk_bf16_f32 v45, v10, v11
	v_lshlrev_b64 v[10:11], 11, v[6:7]
	v_lshl_add_u64 v[10:11], v[8:9], 0, v[10:11]
	global_store_dwordx4 v[10:11], v[42:45], off
	ds_read2_b32 v[10:11], v23 offset0:8 offset1:41
	s_waitcnt lgkmcnt(0)
	v_cvt_pk_bf16_f32 v42, v10, v11
	ds_read2_b32 v[10:11], v23 offset0:74 offset1:107
	s_waitcnt lgkmcnt(0)
	v_cvt_pk_bf16_f32 v43, v10, v11
	ds_read2_b32 v[10:11], v23 offset0:140 offset1:173
	s_waitcnt lgkmcnt(0)
	v_cvt_pk_bf16_f32 v44, v10, v11
	ds_read2_b32 v[10:11], v23 offset0:206 offset1:239
	s_waitcnt lgkmcnt(0)
	v_cvt_pk_bf16_f32 v45, v10, v11
	v_add_u32_e32 v10, 8, v6
	v_ashrrev_i32_e32 v11, 31, v10
	v_lshlrev_b64 v[10:11], 11, v[10:11]
	v_lshl_add_u64 v[10:11], v[8:9], 0, v[10:11]
	global_store_dwordx4 v[10:11], v[42:45], off
	ds_read2_b32 v[10:11], v23 offset0:16 offset1:49
	s_waitcnt lgkmcnt(0)
	v_cvt_pk_bf16_f32 v42, v10, v11
	ds_read2_b32 v[10:11], v23 offset0:82 offset1:115
	s_waitcnt lgkmcnt(0)
	v_cvt_pk_bf16_f32 v43, v10, v11
	ds_read2_b32 v[10:11], v23 offset0:148 offset1:181
	s_waitcnt lgkmcnt(0)
	v_cvt_pk_bf16_f32 v44, v10, v11
	ds_read2_b32 v[10:11], v23 offset0:214 offset1:247
	s_waitcnt lgkmcnt(0)
	v_cvt_pk_bf16_f32 v45, v10, v11
	v_add_u32_e32 v10, 16, v6
	v_ashrrev_i32_e32 v11, 31, v10
	v_lshlrev_b64 v[10:11], 11, v[10:11]
	v_lshl_add_u64 v[10:11], v[8:9], 0, v[10:11]
	v_add_u32_e32 v6, 24, v6
	global_store_dwordx4 v[10:11], v[42:45], off
	ds_read2_b32 v[10:11], v23 offset0:24 offset1:57
	v_ashrrev_i32_e32 v7, 31, v6
	s_waitcnt lgkmcnt(0)
	v_cvt_pk_bf16_f32 v42, v10, v11
	ds_read2_b32 v[10:11], v23 offset0:90 offset1:123
	v_lshlrev_b64 v[6:7], 11, v[6:7]
	s_waitcnt lgkmcnt(0)
	v_cvt_pk_bf16_f32 v43, v10, v11
	ds_read2_b32 v[10:11], v23 offset0:156 offset1:189
	v_lshl_add_u64 v[6:7], v[8:9], 0, v[6:7]
	s_waitcnt lgkmcnt(0)
	v_cvt_pk_bf16_f32 v44, v10, v11
	ds_read2_b32 v[10:11], v23 offset0:222 offset1:255
	s_waitcnt lgkmcnt(0)
	v_cvt_pk_bf16_f32 v45, v10, v11
	global_store_dwordx4 v[6:7], v[42:45], off
	s_waitcnt lgkmcnt(0)
	s_andn2_b64 exec, exec, s[6:7]
	s_cbranch_execnz .LBB0_882

.LBB0_885:
	v_ashrrev_i32_e32 v6, 31, v40
	v_lshrrev_b32_e32 v6, 27, v6
	v_add_u32_e32 v6, v40, v6
	v_ashrrev_i32_e32 v6, 5, v6
	v_lshlrev_b32_e32 v8, 6, v6
	v_lshlrev_b32_e32 v6, 10, v6
	v_sub_u32_e32 v6, v24, v6
	v_or_b32_e32 v42, v8, v15
	v_ashrrev_i32_e32 v7, 31, v6
	v_ashrrev_i32_e32 v43, 31, v42
	v_lshl_add_u64 v[10:11], v[6:7], 2, v[2:3]
	v_lshlrev_b64 v[42:43], 12, v[42:43]
	v_or_b32_e32 v46, v8, v16
	v_lshl_add_u64 v[42:43], v[10:11], 0, v[42:43]
	v_ashrrev_i32_e32 v47, 31, v46
	global_load_dwordx4 v[42:45], v[42:43], off
	v_lshlrev_b64 v[46:47], 12, v[46:47]
	v_lshl_add_u64 v[46:47], v[10:11], 0, v[46:47]
	global_load_dwordx4 v[46:49], v[46:47], off
	v_add_u32_e32 v6, v6, v15
	v_ashrrev_i32_e32 v9, 31, v8
	v_ashrrev_i32_e32 v7, 31, v6
	v_add_u32_e32 v40, s4, v40
	v_cmp_lt_i32_e32 vcc, s6, v40
	v_add_u32_e32 v24, s5, v24
	s_or_b64 s[2:3], vcc, s[2:3]
	v_or_b32_e32 v226, v8, v17
	v_ashrrev_i32_e32 v227, 31, v226
	v_lshlrev_b64 v[226:227], 12, v[226:227]
	v_or_b32_e32 v230, v8, v18
	v_lshl_add_u64 v[226:227], v[10:11], 0, v[226:227]
	v_ashrrev_i32_e32 v231, 31, v230
	global_load_dwordx4 v[226:229], v[226:227], off
	v_lshlrev_b64 v[230:231], 12, v[230:231]
	v_lshl_add_u64 v[230:231], v[10:11], 0, v[230:231]
	global_load_dwordx4 v[230:233], v[230:231], off
	v_or_b32_e32 v234, v8, v19
	v_ashrrev_i32_e32 v235, 31, v234
	v_lshlrev_b64 v[234:235], 12, v[234:235]
	v_or_b32_e32 v238, v8, v20
	v_lshl_add_u64 v[234:235], v[10:11], 0, v[234:235]
	v_ashrrev_i32_e32 v239, 31, v238
	global_load_dwordx4 v[234:237], v[234:235], off
	v_lshlrev_b64 v[238:239], 12, v[238:239]
	v_lshl_add_u64 v[238:239], v[10:11], 0, v[238:239]
	global_load_dwordx4 v[238:241], v[238:239], off
	v_or_b32_e32 v242, v8, v21
	v_ashrrev_i32_e32 v243, 31, v242
	v_lshlrev_b64 v[242:243], 12, v[242:243]
	v_or_b32_e32 v246, v8, v22
	v_lshl_add_u64 v[242:243], v[10:11], 0, v[242:243]
	v_ashrrev_i32_e32 v247, 31, v246
	global_load_dwordx4 v[242:245], v[242:243], off
	v_lshlrev_b64 v[246:247], 12, v[246:247]
	v_lshl_add_u64 v[10:11], v[10:11], 0, v[246:247]
	global_load_dwordx4 v[246:249], v[10:11], off
	v_lshl_add_u64 v[8:9], v[8:9], 1, v[4:5]
	s_waitcnt vmcnt(7)
	ds_write2_b32 v25, v42, v43 offset1:1
	ds_write2_b32 v25, v44, v45 offset0:2 offset1:3
	s_waitcnt vmcnt(6)
	ds_write2_b32 v26, v46, v47 offset1:1
	ds_write2_b32 v27, v48, v49 offset1:1
	s_waitcnt vmcnt(5)
	ds_write2_b32 v28, v226, v227 offset1:1
	ds_write2_b32 v29, v228, v229 offset1:1
	s_waitcnt vmcnt(4)
	ds_write2_b32 v30, v230, v231 offset1:1
	ds_write2_b32 v31, v232, v233 offset1:1
	s_waitcnt lgkmcnt(7)
	s_waitcnt vmcnt(3)
	ds_write2_b32 v32, v234, v235 offset1:1
	ds_write2_b32 v33, v236, v237 offset1:1
	s_waitcnt vmcnt(2)
	ds_write2_b32 v34, v238, v239 offset1:1
	ds_write2_b32 v35, v240, v241 offset1:1
	s_waitcnt vmcnt(1)
	ds_write2_b32 v36, v242, v243 offset1:1
	ds_write2_b32 v37, v244, v245 offset1:1
	s_waitcnt vmcnt(0)
	ds_write2_b32 v38, v246, v247 offset1:1
	ds_write2_b32 v39, v248, v249 offset1:1
	s_waitcnt lgkmcnt(0)
	ds_read2_b32 v[10:11], v23 offset1:33
	s_waitcnt lgkmcnt(0)
	v_cvt_pk_bf16_f32 v42, v10, v11
	ds_read2_b32 v[10:11], v23 offset0:66 offset1:99
	s_waitcnt lgkmcnt(0)
	v_cvt_pk_bf16_f32 v43, v10, v11
	ds_read2_b32 v[10:11], v23 offset0:132 offset1:165
	s_waitcnt lgkmcnt(0)
	v_cvt_pk_bf16_f32 v44, v10, v11
	ds_read2_b32 v[10:11], v23 offset0:198 offset1:231
	s_waitcnt lgkmcnt(0)
	v_cvt_pk_bf16_f32 v45, v10, v11
	v_lshlrev_b64 v[10:11], 13, v[6:7]
	v_lshl_add_u64 v[10:11], v[8:9], 0, v[10:11]
	global_store_dwordx4 v[10:11], v[42:45], off
	ds_read2_b32 v[10:11], v23 offset0:8 offset1:41
	s_waitcnt lgkmcnt(0)
	v_cvt_pk_bf16_f32 v42, v10, v11
	ds_read2_b32 v[10:11], v23 offset0:74 offset1:107
	s_waitcnt lgkmcnt(0)
	v_cvt_pk_bf16_f32 v43, v10, v11
	ds_read2_b32 v[10:11], v23 offset0:140 offset1:173
	s_waitcnt lgkmcnt(0)
	v_cvt_pk_bf16_f32 v44, v10, v11
	ds_read2_b32 v[10:11], v23 offset0:206 offset1:239
	s_waitcnt lgkmcnt(0)
	v_cvt_pk_bf16_f32 v45, v10, v11
	v_add_u32_e32 v10, 8, v6
	v_ashrrev_i32_e32 v11, 31, v10
	v_lshlrev_b64 v[10:11], 13, v[10:11]
	v_lshl_add_u64 v[10:11], v[8:9], 0, v[10:11]
	global_store_dwordx4 v[10:11], v[42:45], off
	ds_read2_b32 v[10:11], v23 offset0:16 offset1:49
	s_waitcnt lgkmcnt(0)
	v_cvt_pk_bf16_f32 v42, v10, v11
	ds_read2_b32 v[10:11], v23 offset0:82 offset1:115
	s_waitcnt lgkmcnt(0)
	v_cvt_pk_bf16_f32 v43, v10, v11
	ds_read2_b32 v[10:11], v23 offset0:148 offset1:181
	s_waitcnt lgkmcnt(0)
	v_cvt_pk_bf16_f32 v44, v10, v11
	ds_read2_b32 v[10:11], v23 offset0:214 offset1:247
	s_waitcnt lgkmcnt(0)
	v_cvt_pk_bf16_f32 v45, v10, v11
	v_add_u32_e32 v10, 16, v6
	v_ashrrev_i32_e32 v11, 31, v10
	v_lshlrev_b64 v[10:11], 13, v[10:11]
	v_lshl_add_u64 v[10:11], v[8:9], 0, v[10:11]
	v_add_u32_e32 v6, 24, v6
	global_store_dwordx4 v[10:11], v[42:45], off
	ds_read2_b32 v[10:11], v23 offset0:24 offset1:57
	v_ashrrev_i32_e32 v7, 31, v6
	s_waitcnt lgkmcnt(0)
	v_cvt_pk_bf16_f32 v42, v10, v11
	ds_read2_b32 v[10:11], v23 offset0:90 offset1:123
	v_lshlrev_b64 v[6:7], 13, v[6:7]
	s_waitcnt lgkmcnt(0)
	v_cvt_pk_bf16_f32 v43, v10, v11
	ds_read2_b32 v[10:11], v23 offset0:156 offset1:189
	v_lshl_add_u64 v[6:7], v[8:9], 0, v[6:7]
	s_waitcnt lgkmcnt(0)
	v_cvt_pk_bf16_f32 v44, v10, v11
	ds_read2_b32 v[10:11], v23 offset0:222 offset1:255
	s_waitcnt lgkmcnt(0)
	v_cvt_pk_bf16_f32 v45, v10, v11
	global_store_dwordx4 v[6:7], v[42:45], off
	s_waitcnt lgkmcnt(0)
	s_andn2_b64 exec, exec, s[2:3]
	s_cbranch_execnz .LBB0_885

.LBB0_888:
	v_ashrrev_i32_e32 v6, 31, v40
	v_lshrrev_b32_e32 v6, 27, v6
	v_add_u32_e32 v6, v40, v6
	v_ashrrev_i32_e32 v6, 5, v6
	v_lshlrev_b32_e32 v8, 6, v6
	v_lshlrev_b32_e32 v6, 10, v6
	v_sub_u32_e32 v6, v24, v6
	v_or_b32_e32 v42, v8, v15
	v_ashrrev_i32_e32 v7, 31, v6
	v_ashrrev_i32_e32 v43, 31, v42
	v_lshl_add_u64 v[10:11], v[6:7], 2, v[2:3]
	v_lshlrev_b64 v[42:43], 12, v[42:43]
	v_or_b32_e32 v46, v8, v16
	v_lshl_add_u64 v[42:43], v[10:11], 0, v[42:43]
	v_ashrrev_i32_e32 v47, 31, v46
	global_load_dwordx4 v[42:45], v[42:43], off
	v_lshlrev_b64 v[46:47], 12, v[46:47]
	v_lshl_add_u64 v[46:47], v[10:11], 0, v[46:47]
	global_load_dwordx4 v[46:49], v[46:47], off
	v_add_u32_e32 v6, v6, v15
	v_ashrrev_i32_e32 v9, 31, v8
	v_ashrrev_i32_e32 v7, 31, v6
	v_add_u32_e32 v40, s4, v40
	s_movk_i32 s0, 0x1ff
	v_cmp_lt_i32_e64 s[0:1], s0, v40
	v_add_u32_e32 v24, s5, v24
	s_or_b64 s[6:7], s[0:1], s[6:7]
	v_or_b32_e32 v226, v8, v17
	v_ashrrev_i32_e32 v227, 31, v226
	v_lshlrev_b64 v[226:227], 12, v[226:227]
	v_or_b32_e32 v230, v8, v18
	v_lshl_add_u64 v[226:227], v[10:11], 0, v[226:227]
	v_ashrrev_i32_e32 v231, 31, v230
	global_load_dwordx4 v[226:229], v[226:227], off
	v_lshlrev_b64 v[230:231], 12, v[230:231]
	v_lshl_add_u64 v[230:231], v[10:11], 0, v[230:231]
	global_load_dwordx4 v[230:233], v[230:231], off
	v_or_b32_e32 v234, v8, v19
	v_ashrrev_i32_e32 v235, 31, v234
	v_lshlrev_b64 v[234:235], 12, v[234:235]
	v_or_b32_e32 v238, v8, v20
	v_lshl_add_u64 v[234:235], v[10:11], 0, v[234:235]
	v_ashrrev_i32_e32 v239, 31, v238
	global_load_dwordx4 v[234:237], v[234:235], off
	v_lshlrev_b64 v[238:239], 12, v[238:239]
	v_lshl_add_u64 v[238:239], v[10:11], 0, v[238:239]
	global_load_dwordx4 v[238:241], v[238:239], off
	v_or_b32_e32 v242, v8, v21
	v_ashrrev_i32_e32 v243, 31, v242
	v_lshlrev_b64 v[242:243], 12, v[242:243]
	v_or_b32_e32 v246, v8, v22
	v_lshl_add_u64 v[242:243], v[10:11], 0, v[242:243]
	v_ashrrev_i32_e32 v247, 31, v246
	global_load_dwordx4 v[242:245], v[242:243], off
	v_lshlrev_b64 v[246:247], 12, v[246:247]
	v_lshl_add_u64 v[10:11], v[10:11], 0, v[246:247]
	global_load_dwordx4 v[246:249], v[10:11], off
	v_lshl_add_u64 v[8:9], v[8:9], 1, v[4:5]
	s_waitcnt vmcnt(7)
	ds_write2_b32 v25, v42, v43 offset1:1
	ds_write2_b32 v25, v44, v45 offset0:2 offset1:3
	s_waitcnt vmcnt(6)
	ds_write2_b32 v26, v46, v47 offset1:1
	ds_write2_b32 v27, v48, v49 offset1:1
	s_waitcnt vmcnt(5)
	ds_write2_b32 v28, v226, v227 offset1:1
	ds_write2_b32 v29, v228, v229 offset1:1
	s_waitcnt vmcnt(4)
	ds_write2_b32 v30, v230, v231 offset1:1
	ds_write2_b32 v31, v232, v233 offset1:1
	s_waitcnt lgkmcnt(7)
	s_waitcnt vmcnt(3)
	ds_write2_b32 v32, v234, v235 offset1:1
	ds_write2_b32 v33, v236, v237 offset1:1
	s_waitcnt vmcnt(2)
	ds_write2_b32 v34, v238, v239 offset1:1
	ds_write2_b32 v35, v240, v241 offset1:1
	s_waitcnt vmcnt(1)
	ds_write2_b32 v36, v242, v243 offset1:1
	ds_write2_b32 v37, v244, v245 offset1:1
	s_waitcnt vmcnt(0)
	ds_write2_b32 v38, v246, v247 offset1:1
	ds_write2_b32 v39, v248, v249 offset1:1
	s_waitcnt lgkmcnt(0)
	ds_read2_b32 v[10:11], v23 offset1:33
	s_waitcnt lgkmcnt(0)
	v_cvt_pk_bf16_f32 v42, v10, v11
	ds_read2_b32 v[10:11], v23 offset0:66 offset1:99
	s_waitcnt lgkmcnt(0)
	v_cvt_pk_bf16_f32 v43, v10, v11
	ds_read2_b32 v[10:11], v23 offset0:132 offset1:165
	s_waitcnt lgkmcnt(0)
	v_cvt_pk_bf16_f32 v44, v10, v11
	ds_read2_b32 v[10:11], v23 offset0:198 offset1:231
	s_waitcnt lgkmcnt(0)
	v_cvt_pk_bf16_f32 v45, v10, v11
	v_lshlrev_b64 v[10:11], 11, v[6:7]
	v_lshl_add_u64 v[10:11], v[8:9], 0, v[10:11]
	global_store_dwordx4 v[10:11], v[42:45], off
	ds_read2_b32 v[10:11], v23 offset0:8 offset1:41
	s_waitcnt lgkmcnt(0)
	v_cvt_pk_bf16_f32 v42, v10, v11
	ds_read2_b32 v[10:11], v23 offset0:74 offset1:107
	s_waitcnt lgkmcnt(0)
	v_cvt_pk_bf16_f32 v43, v10, v11
	ds_read2_b32 v[10:11], v23 offset0:140 offset1:173
	s_waitcnt lgkmcnt(0)
	v_cvt_pk_bf16_f32 v44, v10, v11
	ds_read2_b32 v[10:11], v23 offset0:206 offset1:239
	s_waitcnt lgkmcnt(0)
	v_cvt_pk_bf16_f32 v45, v10, v11
	v_add_u32_e32 v10, 8, v6
	v_ashrrev_i32_e32 v11, 31, v10
	v_lshlrev_b64 v[10:11], 11, v[10:11]
	v_lshl_add_u64 v[10:11], v[8:9], 0, v[10:11]
	global_store_dwordx4 v[10:11], v[42:45], off
	ds_read2_b32 v[10:11], v23 offset0:16 offset1:49
	s_waitcnt lgkmcnt(0)
	v_cvt_pk_bf16_f32 v42, v10, v11
	ds_read2_b32 v[10:11], v23 offset0:82 offset1:115
	s_waitcnt lgkmcnt(0)
	v_cvt_pk_bf16_f32 v43, v10, v11
	ds_read2_b32 v[10:11], v23 offset0:148 offset1:181
	s_waitcnt lgkmcnt(0)
	v_cvt_pk_bf16_f32 v44, v10, v11
	ds_read2_b32 v[10:11], v23 offset0:214 offset1:247
	s_waitcnt lgkmcnt(0)
	v_cvt_pk_bf16_f32 v45, v10, v11
	v_add_u32_e32 v10, 16, v6
	v_ashrrev_i32_e32 v11, 31, v10
	v_lshlrev_b64 v[10:11], 11, v[10:11]
	v_lshl_add_u64 v[10:11], v[8:9], 0, v[10:11]
	v_add_u32_e32 v6, 24, v6
	global_store_dwordx4 v[10:11], v[42:45], off
	ds_read2_b32 v[10:11], v23 offset0:24 offset1:57
	v_ashrrev_i32_e32 v7, 31, v6
	s_waitcnt lgkmcnt(0)
	v_cvt_pk_bf16_f32 v42, v10, v11
	ds_read2_b32 v[10:11], v23 offset0:90 offset1:123
	v_lshlrev_b64 v[6:7], 11, v[6:7]
	s_waitcnt lgkmcnt(0)
	v_cvt_pk_bf16_f32 v43, v10, v11
	ds_read2_b32 v[10:11], v23 offset0:156 offset1:189
	v_lshl_add_u64 v[6:7], v[8:9], 0, v[6:7]
	s_waitcnt lgkmcnt(0)
	v_cvt_pk_bf16_f32 v44, v10, v11
	ds_read2_b32 v[10:11], v23 offset0:222 offset1:255
	s_waitcnt lgkmcnt(0)
	v_cvt_pk_bf16_f32 v45, v10, v11
	global_store_dwordx4 v[6:7], v[42:45], off
	s_waitcnt lgkmcnt(0)
	s_andn2_b64 exec, exec, s[6:7]
	s_cbranch_execnz .LBB0_888

.LBB0_894:
	v_ashrrev_i32_e32 v6, 31, v12
	v_lshrrev_b32_e32 v6, 27, v6
	v_add_u32_e32 v6, v12, v6
	v_ashrrev_i32_e32 v6, 5, v6
	v_lshlrev_b32_e32 v8, 6, v6
	v_lshlrev_b32_e32 v6, 10, v6
	v_sub_u32_e32 v6, v13, v6
	v_or_b32_e32 v38, v8, v15
	v_ashrrev_i32_e32 v7, 31, v6
	v_ashrrev_i32_e32 v39, 31, v38
	v_lshl_add_u64 v[10:11], v[6:7], 2, v[2:3]
	v_lshlrev_b64 v[38:39], 12, v[38:39]
	v_or_b32_e32 v42, v8, v16
	v_lshl_add_u64 v[38:39], v[10:11], 0, v[38:39]
	v_ashrrev_i32_e32 v43, 31, v42
	global_load_dwordx4 v[38:41], v[38:39], off
	v_lshlrev_b64 v[42:43], 12, v[42:43]
	v_lshl_add_u64 v[42:43], v[10:11], 0, v[42:43]
	global_load_dwordx4 v[42:45], v[42:43], off
	v_add_u32_e32 v6, v6, v15
	v_ashrrev_i32_e32 v9, 31, v8
	v_ashrrev_i32_e32 v7, 31, v6
	v_add_u32_e32 v12, s4, v12
	v_cmp_lt_i32_e32 vcc, s6, v12
	v_add_u32_e32 v13, s5, v13
	s_or_b64 s[2:3], vcc, s[2:3]
	v_or_b32_e32 v226, v8, v17
	v_ashrrev_i32_e32 v227, 31, v226
	v_lshlrev_b64 v[226:227], 12, v[226:227]
	v_or_b32_e32 v230, v8, v18
	v_lshl_add_u64 v[226:227], v[10:11], 0, v[226:227]
	v_ashrrev_i32_e32 v231, 31, v230
	global_load_dwordx4 v[226:229], v[226:227], off
	v_lshlrev_b64 v[230:231], 12, v[230:231]
	v_lshl_add_u64 v[230:231], v[10:11], 0, v[230:231]
	global_load_dwordx4 v[230:233], v[230:231], off
	v_or_b32_e32 v234, v8, v19
	v_ashrrev_i32_e32 v235, 31, v234
	v_lshlrev_b64 v[234:235], 12, v[234:235]
	v_or_b32_e32 v238, v8, v20
	v_lshl_add_u64 v[234:235], v[10:11], 0, v[234:235]
	v_ashrrev_i32_e32 v239, 31, v238
	global_load_dwordx4 v[234:237], v[234:235], off
	v_lshlrev_b64 v[238:239], 12, v[238:239]
	v_lshl_add_u64 v[238:239], v[10:11], 0, v[238:239]
	global_load_dwordx4 v[238:241], v[238:239], off
	v_or_b32_e32 v242, v8, v21
	v_ashrrev_i32_e32 v243, 31, v242
	v_lshlrev_b64 v[242:243], 12, v[242:243]
	v_or_b32_e32 v246, v8, v22
	v_lshl_add_u64 v[242:243], v[10:11], 0, v[242:243]
	v_ashrrev_i32_e32 v247, 31, v246
	global_load_dwordx4 v[242:245], v[242:243], off
	v_lshlrev_b64 v[246:247], 12, v[246:247]
	v_lshl_add_u64 v[10:11], v[10:11], 0, v[246:247]
	global_load_dwordx4 v[246:249], v[10:11], off
	v_lshl_add_u64 v[8:9], v[8:9], 1, v[4:5]
	s_waitcnt vmcnt(7)
	ds_write2_b32 v23, v38, v39 offset1:1
	ds_write2_b32 v23, v40, v41 offset0:2 offset1:3
	s_waitcnt vmcnt(6)
	ds_write2_b32 v24, v42, v43 offset1:1
	ds_write2_b32 v25, v44, v45 offset1:1
	s_waitcnt vmcnt(5)
	ds_write2_b32 v26, v226, v227 offset1:1
	ds_write2_b32 v27, v228, v229 offset1:1
	s_waitcnt vmcnt(4)
	ds_write2_b32 v28, v230, v231 offset1:1
	ds_write2_b32 v29, v232, v233 offset1:1
	s_waitcnt lgkmcnt(7)
	s_waitcnt vmcnt(3)
	ds_write2_b32 v30, v234, v235 offset1:1
	ds_write2_b32 v31, v236, v237 offset1:1
	s_waitcnt vmcnt(2)
	ds_write2_b32 v32, v238, v239 offset1:1
	ds_write2_b32 v33, v240, v241 offset1:1
	s_waitcnt vmcnt(1)
	ds_write2_b32 v34, v242, v243 offset1:1
	ds_write2_b32 v35, v244, v245 offset1:1
	s_waitcnt vmcnt(0)
	ds_write2_b32 v36, v246, v247 offset1:1
	ds_write2_b32 v37, v248, v249 offset1:1
	s_waitcnt lgkmcnt(0)
	ds_read2_b32 v[10:11], v14 offset1:33
	s_waitcnt lgkmcnt(0)
	v_cvt_pk_bf16_f32 v38, v10, v11
	ds_read2_b32 v[10:11], v14 offset0:66 offset1:99
	s_waitcnt lgkmcnt(0)
	v_cvt_pk_bf16_f32 v39, v10, v11
	ds_read2_b32 v[10:11], v14 offset0:132 offset1:165
	s_waitcnt lgkmcnt(0)
	v_cvt_pk_bf16_f32 v40, v10, v11
	ds_read2_b32 v[10:11], v14 offset0:198 offset1:231
	s_waitcnt lgkmcnt(0)
	v_cvt_pk_bf16_f32 v41, v10, v11
	v_lshlrev_b64 v[10:11], 11, v[6:7]
	v_lshl_add_u64 v[10:11], v[8:9], 0, v[10:11]
	global_store_dwordx4 v[10:11], v[38:41], off
	ds_read2_b32 v[10:11], v14 offset0:8 offset1:41
	s_waitcnt lgkmcnt(0)
	v_cvt_pk_bf16_f32 v38, v10, v11
	ds_read2_b32 v[10:11], v14 offset0:74 offset1:107
	s_waitcnt lgkmcnt(0)
	v_cvt_pk_bf16_f32 v39, v10, v11
	ds_read2_b32 v[10:11], v14 offset0:140 offset1:173
	s_waitcnt lgkmcnt(0)
	v_cvt_pk_bf16_f32 v40, v10, v11
	ds_read2_b32 v[10:11], v14 offset0:206 offset1:239
	s_waitcnt lgkmcnt(0)
	v_cvt_pk_bf16_f32 v41, v10, v11
	v_add_u32_e32 v10, 8, v6
	v_ashrrev_i32_e32 v11, 31, v10
	v_lshlrev_b64 v[10:11], 11, v[10:11]
	v_lshl_add_u64 v[10:11], v[8:9], 0, v[10:11]
	global_store_dwordx4 v[10:11], v[38:41], off
	ds_read2_b32 v[10:11], v14 offset0:16 offset1:49
	s_waitcnt lgkmcnt(0)
	v_cvt_pk_bf16_f32 v38, v10, v11
	ds_read2_b32 v[10:11], v14 offset0:82 offset1:115
	s_waitcnt lgkmcnt(0)
	v_cvt_pk_bf16_f32 v39, v10, v11
	ds_read2_b32 v[10:11], v14 offset0:148 offset1:181
	s_waitcnt lgkmcnt(0)
	v_cvt_pk_bf16_f32 v40, v10, v11
	ds_read2_b32 v[10:11], v14 offset0:214 offset1:247
	s_waitcnt lgkmcnt(0)
	v_cvt_pk_bf16_f32 v41, v10, v11
	v_add_u32_e32 v10, 16, v6
	v_ashrrev_i32_e32 v11, 31, v10
	v_lshlrev_b64 v[10:11], 11, v[10:11]
	v_lshl_add_u64 v[10:11], v[8:9], 0, v[10:11]
	v_add_u32_e32 v6, 24, v6
	global_store_dwordx4 v[10:11], v[38:41], off
	ds_read2_b32 v[10:11], v14 offset0:24 offset1:57
	v_ashrrev_i32_e32 v7, 31, v6
	s_waitcnt lgkmcnt(0)
	v_cvt_pk_bf16_f32 v38, v10, v11
	ds_read2_b32 v[10:11], v14 offset0:90 offset1:123
	v_lshlrev_b64 v[6:7], 11, v[6:7]
	s_waitcnt lgkmcnt(0)
	v_cvt_pk_bf16_f32 v39, v10, v11
	ds_read2_b32 v[10:11], v14 offset0:156 offset1:189
	v_lshl_add_u64 v[6:7], v[8:9], 0, v[6:7]
	s_waitcnt lgkmcnt(0)
	v_cvt_pk_bf16_f32 v40, v10, v11
	ds_read2_b32 v[10:11], v14 offset0:222 offset1:255
	s_waitcnt lgkmcnt(0)
	v_cvt_pk_bf16_f32 v41, v10, v11
	global_store_dwordx4 v[6:7], v[38:41], off
	s_waitcnt lgkmcnt(0)
	s_andn2_b64 exec, exec, s[2:3]
	s_cbranch_execnz .LBB0_894

.LBB0_976:
.LBB0_977:
	v_lshl_or_b32 v144, s20, 8, v135
	v_lshl_add_u32 v186, s18, 8, v134
	v_ashrrev_i32_e32 v145, 31, v144
	v_lshlrev_b64 v[144:145], 2, v[144:145]
	v_ashrrev_i32_e32 v187, 31, v186
	v_lshl_add_u64 v[146:147], s[88:89], 0, v[144:145]
	v_lshlrev_b64 v[148:149], 12, v[186:187]
	v_or_b32_e32 v170, 16, v186
	v_lshl_add_u64 v[166:167], v[146:147], 0, v[148:149]
	v_ashrrev_i32_e32 v171, 31, v170
	v_mov_b64_e32 v[224:225], v[166:167]
	global_load_dwordx4 v[154:157], v[166:167], off
	global_load_dwordx4 v[158:161], v[166:167], off offset:64
	global_load_dwordx4 v[162:165], v[166:167], off offset:512
	s_nop 0
	global_load_dwordx4 v[166:169], v[166:167], off offset:576
	v_lshlrev_b64 v[188:189], 12, v[170:171]
	v_lshl_add_u64 v[182:183], v[146:147], 0, v[188:189]
	global_load_dwordx4 v[170:173], v[182:183], off
	global_load_dwordx4 v[174:177], v[182:183], off offset:64
	global_load_dwordx4 v[178:181], v[182:183], off offset:512
	s_nop 0
	global_load_dwordx4 v[182:185], v[182:183], off offset:576
	v_add_co_u32_e32 v226, vcc, 0x20000, v224
	s_nop 1
	v_addc_co_u32_e32 v227, vcc, 0, v225, vcc
	v_add_co_u32_e32 v228, vcc, 0x30000, v224
	s_nop 1
	v_addc_co_u32_e32 v229, vcc, 0, v225, vcc
	global_load_dwordx4 v[192:195], v[226:227], off
	global_load_dwordx4 v[196:199], v[226:227], off offset:64
	global_load_dwordx4 v[200:203], v[226:227], off offset:512
	global_load_dwordx4 v[204:207], v[226:227], off offset:576
	global_load_dwordx4 v[208:211], v[228:229], off
	global_load_dwordx4 v[212:215], v[228:229], off offset:64
	global_load_dwordx4 v[216:219], v[228:229], off offset:512
	global_load_dwordx4 v[220:223], v[228:229], off offset:576
	v_lshl_add_u64 v[190:191], s[88:89], 0, v[148:149]
	v_lshl_add_u64 v[190:191], v[190:191], 0, v[144:145]
	s_mov_b64 s[22:23], 0x80000
	s_waitcnt vmcnt(8)
	v_pk_add_f32 v[128:129], v[128:129], v[156:157]
	v_pk_add_f32 v[126:127], v[126:127], v[154:155]
	v_pk_add_f32 v[112:113], v[112:113], v[164:165]
	v_pk_add_f32 v[108:109], v[108:109], v[168:169]
	v_pk_add_f32 v[106:107], v[106:107], v[166:167]
	v_pk_add_f32 v[110:111], v[110:111], v[162:163]
	global_store_dwordx4 v[190:191], v[106:109], off offset:576
	global_store_dwordx4 v[190:191], v[110:113], off offset:512
	v_pk_add_f32 v[100:101], v[100:101], v[184:185]
	v_lshl_add_u64 v[106:107], s[88:89], 0, v[188:189]
	v_lshl_add_u64 v[110:111], v[106:107], 0, v[144:145]
	v_pk_add_f32 v[98:99], v[98:99], v[182:183]
	global_store_dwordx4 v[110:111], v[98:101], off offset:576
	v_pk_add_f32 v[108:109], v[120:121], v[172:173]
	v_pk_add_f32 v[106:107], v[118:119], v[170:171]
	v_or_b32_e32 v98, 32, v186
	v_ashrrev_i32_e32 v99, 31, v98
	v_pk_add_f32 v[124:125], v[124:125], v[160:161]
	v_pk_add_f32 v[122:123], v[122:123], v[158:159]
	global_store_dwordx4 v[110:111], v[106:109], off
	v_pk_add_f32 v[104:105], v[104:105], v[180:181]
	v_pk_add_f32 v[102:103], v[102:103], v[178:179]
	v_pk_add_f32 v[108:109], v[116:117], v[176:177]
	v_pk_add_f32 v[106:107], v[114:115], v[174:175]
	v_lshlrev_b64 v[154:155], 12, v[98:99]
	global_store_dwordx4 v[190:191], v[126:129], off
	global_store_dwordx4 v[190:191], v[122:125], off offset:64
	global_store_dwordx4 v[110:111], v[106:109], off offset:64
	global_store_dwordx4 v[110:111], v[102:105], off offset:512
	v_lshl_add_u64 v[110:111], v[146:147], 0, v[154:155]
	v_or_b32_e32 v114, 48, v186
	s_nop 0
	v_ashrrev_i32_e32 v115, 31, v114
	v_lshlrev_b64 v[156:157], 12, v[114:115]
	v_lshl_add_u64 v[126:127], v[146:147], 0, v[156:157]
	s_nop 0
	s_nop 1
	s_waitcnt vmcnt(8)
	v_mov_b64_e32 v[98:99], v[192:193]
	v_mov_b64_e32 v[100:101], v[194:195]
	v_mov_b64_e32 v[102:103], v[196:197]
	v_mov_b64_e32 v[104:105], v[198:199]
	v_mov_b64_e32 v[106:107], v[200:201]
	v_mov_b64_e32 v[108:109], v[202:203]
	v_mov_b64_e32 v[110:111], v[204:205]
	v_mov_b64_e32 v[112:113], v[206:207]
	v_mov_b64_e32 v[114:115], v[208:209]
	v_mov_b64_e32 v[116:117], v[210:211]
	v_mov_b64_e32 v[118:119], v[212:213]
	v_mov_b64_e32 v[120:121], v[214:215]
	v_mov_b64_e32 v[122:123], v[216:217]
	v_mov_b64_e32 v[124:125], v[218:219]
	v_mov_b64_e32 v[126:127], v[220:221]
	v_mov_b64_e32 v[128:129], v[222:223]
	v_add_co_u32_e32 v226, vcc, 0x80000, v224
	s_nop 1
	v_addc_co_u32_e32 v227, vcc, 0, v225, vcc
	v_add_co_u32_e32 v228, vcc, 0x90000, v224
	s_nop 1
	v_addc_co_u32_e32 v229, vcc, 0, v225, vcc
	global_load_dwordx4 v[192:195], v[226:227], off
	global_load_dwordx4 v[196:199], v[226:227], off offset:64
	global_load_dwordx4 v[200:203], v[226:227], off offset:512
	global_load_dwordx4 v[204:207], v[226:227], off offset:576
	global_load_dwordx4 v[208:211], v[228:229], off
	global_load_dwordx4 v[212:215], v[228:229], off offset:64
	global_load_dwordx4 v[216:219], v[228:229], off offset:512
	global_load_dwordx4 v[220:223], v[228:229], off offset:576
	v_lshl_add_u64 v[154:155], s[88:89], 0, v[154:155]
	v_lshl_add_u64 v[154:155], v[154:155], 0, v[144:145]
	v_pk_add_f32 v[96:97], v[96:97], v[100:101]
	v_pk_add_f32 v[94:95], v[94:95], v[98:99]
	v_pk_add_f32 v[80:81], v[80:81], v[108:109]
	v_pk_add_f32 v[76:77], v[76:77], v[112:113]
	v_pk_add_f32 v[74:75], v[74:75], v[110:111]
	v_pk_add_f32 v[78:79], v[78:79], v[106:107]
	global_store_dwordx4 v[154:155], v[74:77], off offset:576
	global_store_dwordx4 v[154:155], v[78:81], off offset:512
	v_pk_add_f32 v[92:93], v[92:93], v[104:105]
	v_lshl_add_u64 v[74:75], s[88:89], 0, v[156:157]
	v_lshl_add_u64 v[78:79], v[74:75], 0, v[144:145]
	v_pk_add_f32 v[76:77], v[88:89], v[116:117]
	v_pk_add_f32 v[74:75], v[86:87], v[114:115]
	v_pk_add_f32 v[90:91], v[90:91], v[102:103]
	global_store_dwordx4 v[78:79], v[74:77], off
	v_pk_add_f32 v[72:73], v[72:73], v[124:125]
	v_pk_add_f32 v[70:71], v[70:71], v[122:123]
	v_pk_add_f32 v[76:77], v[84:85], v[120:121]
	v_pk_add_f32 v[74:75], v[82:83], v[118:119]
	v_pk_add_f32 v[68:69], v[68:69], v[128:129]
	v_pk_add_f32 v[66:67], v[66:67], v[126:127]
	v_lshl_add_u64 v[98:99], v[148:149], 0, s[22:23]
	global_store_dwordx4 v[154:155], v[94:97], off
	global_store_dwordx4 v[154:155], v[90:93], off offset:64
	global_store_dwordx4 v[78:79], v[74:77], off offset:64
	global_store_dwordx4 v[78:79], v[70:73], off offset:512
	global_store_dwordx4 v[78:79], v[66:69], off offset:576
	v_lshl_add_u64 v[78:79], v[146:147], 0, v[98:99]
	s_nop 0
	s_mov_b64 s[22:23], 0x90000
	v_lshl_add_u64 v[100:101], v[148:149], 0, s[22:23]
	v_lshl_add_u64 v[94:95], v[146:147], 0, v[100:101]
	s_nop 0
	s_nop 1
	s_waitcnt vmcnt(8)
	v_mov_b64_e32 v[66:67], v[192:193]
	v_mov_b64_e32 v[68:69], v[194:195]
	v_mov_b64_e32 v[70:71], v[196:197]
	v_mov_b64_e32 v[72:73], v[198:199]
	v_mov_b64_e32 v[74:75], v[200:201]
	v_mov_b64_e32 v[76:77], v[202:203]
	v_mov_b64_e32 v[78:79], v[204:205]
	v_mov_b64_e32 v[80:81], v[206:207]
	v_mov_b64_e32 v[82:83], v[208:209]
	v_mov_b64_e32 v[84:85], v[210:211]
	v_mov_b64_e32 v[86:87], v[212:213]
	v_mov_b64_e32 v[88:89], v[214:215]
	v_mov_b64_e32 v[90:91], v[216:217]
	v_mov_b64_e32 v[92:93], v[218:219]
	v_mov_b64_e32 v[94:95], v[220:221]
	v_mov_b64_e32 v[96:97], v[222:223]
	v_add_co_u32_e32 v226, vcc, 0xa0000, v224
	s_nop 1
	v_addc_co_u32_e32 v227, vcc, 0, v225, vcc
	v_add_co_u32_e32 v228, vcc, 0xb0000, v224
	s_nop 1
	v_addc_co_u32_e32 v229, vcc, 0, v225, vcc
	global_load_dwordx4 v[192:195], v[226:227], off
	global_load_dwordx4 v[196:199], v[226:227], off offset:64
	global_load_dwordx4 v[200:203], v[226:227], off offset:512
	global_load_dwordx4 v[204:207], v[226:227], off offset:576
	global_load_dwordx4 v[208:211], v[228:229], off
	global_load_dwordx4 v[212:215], v[228:229], off offset:64
	global_load_dwordx4 v[216:219], v[228:229], off offset:512
	global_load_dwordx4 v[220:223], v[228:229], off offset:576
	v_lshl_add_u64 v[98:99], s[88:89], 0, v[98:99]
	v_lshl_add_u64 v[98:99], v[98:99], 0, v[144:145]
	s_mov_b64 s[22:23], 0xa0000
	v_pk_add_f32 v[64:65], v[64:65], v[68:69]
	v_pk_add_f32 v[62:63], v[62:63], v[66:67]
	v_pk_add_f32 v[48:49], v[48:49], v[76:77]
	v_pk_add_f32 v[44:45], v[44:45], v[80:81]
	v_pk_add_f32 v[42:43], v[42:43], v[78:79]
	v_pk_add_f32 v[46:47], v[46:47], v[74:75]
	global_store_dwordx4 v[98:99], v[42:45], off offset:576
	global_store_dwordx4 v[98:99], v[46:49], off offset:512
	v_pk_add_f32 v[60:61], v[60:61], v[72:73]
	v_lshl_add_u64 v[42:43], s[88:89], 0, v[100:101]
	v_lshl_add_u64 v[46:47], v[42:43], 0, v[144:145]
	v_pk_add_f32 v[44:45], v[56:57], v[84:85]
	v_pk_add_f32 v[42:43], v[54:55], v[82:83]
	v_pk_add_f32 v[58:59], v[58:59], v[70:71]
	global_store_dwordx4 v[46:47], v[42:45], off
	v_pk_add_f32 v[40:41], v[40:41], v[92:93]
	v_pk_add_f32 v[38:39], v[38:39], v[90:91]
	v_pk_add_f32 v[44:45], v[52:53], v[88:89]
	v_pk_add_f32 v[42:43], v[50:51], v[86:87]
	v_pk_add_f32 v[36:37], v[36:37], v[96:97]
	v_pk_add_f32 v[34:35], v[34:35], v[94:95]
	v_lshl_add_u64 v[66:67], v[148:149], 0, s[22:23]
	global_store_dwordx4 v[98:99], v[62:65], off
	global_store_dwordx4 v[98:99], v[58:61], off offset:64
	global_store_dwordx4 v[46:47], v[42:45], off offset:64
	global_store_dwordx4 v[46:47], v[38:41], off offset:512
	global_store_dwordx4 v[46:47], v[34:37], off offset:576
	s_mov_b64 s[22:23], 0xb0000
	v_lshl_add_u64 v[68:69], v[148:149], 0, s[22:23]
	v_lshl_add_u64 v[34:35], v[146:147], 0, v[66:67]
	s_nop 0
	v_lshl_add_u64 v[62:63], v[146:147], 0, v[68:69]
	s_nop 0
	s_nop 1
	s_waitcnt vmcnt(8)
	v_mov_b64_e32 v[46:47], v[192:193]
	v_mov_b64_e32 v[48:49], v[194:195]
	v_mov_b64_e32 v[42:43], v[196:197]
	v_mov_b64_e32 v[44:45], v[198:199]
	v_mov_b64_e32 v[38:39], v[200:201]
	v_mov_b64_e32 v[40:41], v[202:203]
	v_mov_b64_e32 v[34:35], v[204:205]
	v_mov_b64_e32 v[36:37], v[206:207]
	v_mov_b64_e32 v[58:59], v[208:209]
	v_mov_b64_e32 v[60:61], v[210:211]
	v_mov_b64_e32 v[54:55], v[212:213]
	v_mov_b64_e32 v[56:57], v[214:215]
	v_mov_b64_e32 v[50:51], v[216:217]
	v_mov_b64_e32 v[52:53], v[218:219]
	v_mov_b64_e32 v[62:63], v[220:221]
	v_mov_b64_e32 v[64:65], v[222:223]
	v_lshl_add_u64 v[66:67], s[88:89], 0, v[66:67]
	v_lshl_add_u64 v[66:67], v[66:67], 0, v[144:145]
	v_pk_add_f32 v[32:33], v[32:33], v[48:49]
	v_pk_add_f32 v[30:31], v[30:31], v[46:47]
	v_pk_add_f32 v[20:21], v[20:21], v[40:41]
	v_pk_add_f32 v[12:13], v[12:13], v[36:37]
	v_pk_add_f32 v[10:11], v[10:11], v[34:35]
	v_pk_add_f32 v[18:19], v[18:19], v[38:39]
	global_store_dwordx4 v[66:67], v[10:13], off offset:576
	global_store_dwordx4 v[66:67], v[18:21], off offset:512
	v_pk_add_f32 v[28:29], v[28:29], v[44:45]
	v_lshl_add_u64 v[10:11], s[88:89], 0, v[68:69]
	v_lshl_add_u64 v[18:19], v[10:11], 0, v[144:145]
	v_pk_add_f32 v[12:13], v[24:25], v[60:61]
	v_pk_add_f32 v[10:11], v[22:23], v[58:59]
	v_pk_add_f32 v[26:27], v[26:27], v[42:43]
	global_store_dwordx4 v[18:19], v[10:13], off
	v_pk_add_f32 v[8:9], v[8:9], v[52:53]
	v_pk_add_f32 v[6:7], v[6:7], v[50:51]
	v_pk_add_f32 v[12:13], v[16:17], v[56:57]
	v_pk_add_f32 v[10:11], v[14:15], v[54:55]
	v_pk_add_f32 v[4:5], v[4:5], v[64:65]
	v_pk_add_f32 v[2:3], v[2:3], v[62:63]
	global_store_dwordx4 v[66:67], v[30:33], off
	global_store_dwordx4 v[66:67], v[26:29], off offset:64
	global_store_dwordx4 v[18:19], v[10:13], off offset:64
	global_store_dwordx4 v[18:19], v[6:9], off offset:512
	global_store_dwordx4 v[18:19], v[2:5], off offset:576
	s_branch .LBB0_962

.LBB0_1203:
	v_ashrrev_i32_e32 v6, 31, v38
	v_lshrrev_b32_e32 v6, 27, v6
	v_add_u32_e32 v6, v38, v6
	v_ashrrev_i32_e32 v6, 5, v6
	v_lshlrev_b32_e32 v8, 6, v6
	v_lshlrev_b32_e32 v6, 10, v6
	v_sub_u32_e32 v6, v21, v6
	v_or_b32_e32 v40, v8, v12
	v_ashrrev_i32_e32 v7, 31, v6
	v_ashrrev_i32_e32 v41, 31, v40
	v_lshl_add_u64 v[10:11], v[6:7], 2, v[2:3]
	v_lshlrev_b64 v[40:41], 12, v[40:41]
	v_or_b32_e32 v44, v8, v13
	v_lshl_add_u64 v[40:41], v[10:11], 0, v[40:41]
	v_ashrrev_i32_e32 v45, 31, v44
	global_load_dwordx4 v[40:43], v[40:41], off
	v_lshlrev_b64 v[44:45], 12, v[44:45]
	v_lshl_add_u64 v[44:45], v[10:11], 0, v[44:45]
	global_load_dwordx4 v[44:47], v[44:45], off
	v_add_u32_e32 v6, v6, v12
	v_ashrrev_i32_e32 v9, 31, v8
	v_ashrrev_i32_e32 v7, 31, v6
	v_add_u32_e32 v38, s0, v38
	v_cmp_lt_i32_e32 vcc, s4, v38
	v_add_u32_e32 v21, s1, v21
	s_or_b64 s[6:7], vcc, s[6:7]
	v_or_b32_e32 v226, v8, v14
	v_ashrrev_i32_e32 v227, 31, v226
	v_lshlrev_b64 v[226:227], 12, v[226:227]
	v_or_b32_e32 v230, v8, v15
	v_lshl_add_u64 v[226:227], v[10:11], 0, v[226:227]
	v_ashrrev_i32_e32 v231, 31, v230
	global_load_dwordx4 v[226:229], v[226:227], off
	v_lshlrev_b64 v[230:231], 12, v[230:231]
	v_lshl_add_u64 v[230:231], v[10:11], 0, v[230:231]
	global_load_dwordx4 v[230:233], v[230:231], off
	v_or_b32_e32 v234, v8, v16
	v_ashrrev_i32_e32 v235, 31, v234
	v_lshlrev_b64 v[234:235], 12, v[234:235]
	v_or_b32_e32 v238, v8, v17
	v_lshl_add_u64 v[234:235], v[10:11], 0, v[234:235]
	v_ashrrev_i32_e32 v239, 31, v238
	global_load_dwordx4 v[234:237], v[234:235], off
	v_lshlrev_b64 v[238:239], 12, v[238:239]
	v_lshl_add_u64 v[238:239], v[10:11], 0, v[238:239]
	global_load_dwordx4 v[238:241], v[238:239], off
	v_or_b32_e32 v242, v8, v18
	v_ashrrev_i32_e32 v243, 31, v242
	v_lshlrev_b64 v[242:243], 12, v[242:243]
	v_or_b32_e32 v246, v8, v19
	v_lshl_add_u64 v[242:243], v[10:11], 0, v[242:243]
	v_ashrrev_i32_e32 v247, 31, v246
	global_load_dwordx4 v[242:245], v[242:243], off
	v_lshlrev_b64 v[246:247], 12, v[246:247]
	v_lshl_add_u64 v[10:11], v[10:11], 0, v[246:247]
	global_load_dwordx4 v[246:249], v[10:11], off
	v_lshl_add_u64 v[8:9], v[8:9], 1, v[4:5]
	s_waitcnt vmcnt(7)
	ds_write2_b32 v23, v40, v41 offset1:1
	ds_write2_b32 v23, v42, v43 offset0:2 offset1:3
	s_waitcnt vmcnt(6)
	ds_write2_b32 v24, v44, v45 offset1:1
	ds_write2_b32 v25, v46, v47 offset1:1
	s_waitcnt vmcnt(5)
	ds_write2_b32 v26, v226, v227 offset1:1
	ds_write2_b32 v27, v228, v229 offset1:1
	s_waitcnt vmcnt(4)
	ds_write2_b32 v28, v230, v231 offset1:1
	ds_write2_b32 v29, v232, v233 offset1:1
	s_waitcnt lgkmcnt(7)
	s_waitcnt vmcnt(3)
	ds_write2_b32 v30, v234, v235 offset1:1
	ds_write2_b32 v31, v236, v237 offset1:1
	s_waitcnt vmcnt(2)
	ds_write2_b32 v32, v238, v239 offset1:1
	ds_write2_b32 v33, v240, v241 offset1:1
	s_waitcnt vmcnt(1)
	ds_write2_b32 v34, v242, v243 offset1:1
	ds_write2_b32 v35, v244, v245 offset1:1
	s_waitcnt vmcnt(0)
	ds_write2_b32 v36, v246, v247 offset1:1
	ds_write2_b32 v37, v248, v249 offset1:1
	s_waitcnt lgkmcnt(0)
	ds_read2_b32 v[10:11], v22 offset1:33
	s_waitcnt lgkmcnt(0)
	v_cvt_pk_bf16_f32 v40, v10, v11
	ds_read2_b32 v[10:11], v22 offset0:66 offset1:99
	s_waitcnt lgkmcnt(0)
	v_cvt_pk_bf16_f32 v41, v10, v11
	ds_read2_b32 v[10:11], v22 offset0:132 offset1:165
	s_waitcnt lgkmcnt(0)
	v_cvt_pk_bf16_f32 v42, v10, v11
	ds_read2_b32 v[10:11], v22 offset0:198 offset1:231
	s_waitcnt lgkmcnt(0)
	v_cvt_pk_bf16_f32 v43, v10, v11
	v_lshlrev_b64 v[10:11], 12, v[6:7]
	v_lshl_add_u64 v[10:11], v[8:9], 0, v[10:11]
	global_store_dwordx4 v[10:11], v[40:43], off
	ds_read2_b32 v[10:11], v22 offset0:8 offset1:41
	s_waitcnt lgkmcnt(0)
	v_cvt_pk_bf16_f32 v40, v10, v11
	ds_read2_b32 v[10:11], v22 offset0:74 offset1:107
	s_waitcnt lgkmcnt(0)
	v_cvt_pk_bf16_f32 v41, v10, v11
	ds_read2_b32 v[10:11], v22 offset0:140 offset1:173
	s_waitcnt lgkmcnt(0)
	v_cvt_pk_bf16_f32 v42, v10, v11
	ds_read2_b32 v[10:11], v22 offset0:206 offset1:239
	s_waitcnt lgkmcnt(0)
	v_cvt_pk_bf16_f32 v43, v10, v11
	v_add_u32_e32 v10, 8, v6
	v_ashrrev_i32_e32 v11, 31, v10
	v_lshlrev_b64 v[10:11], 12, v[10:11]
	v_lshl_add_u64 v[10:11], v[8:9], 0, v[10:11]
	global_store_dwordx4 v[10:11], v[40:43], off
	ds_read2_b32 v[10:11], v22 offset0:16 offset1:49
	s_waitcnt lgkmcnt(0)
	v_cvt_pk_bf16_f32 v40, v10, v11
	ds_read2_b32 v[10:11], v22 offset0:82 offset1:115
	s_waitcnt lgkmcnt(0)
	v_cvt_pk_bf16_f32 v41, v10, v11
	ds_read2_b32 v[10:11], v22 offset0:148 offset1:181
	s_waitcnt lgkmcnt(0)
	v_cvt_pk_bf16_f32 v42, v10, v11
	ds_read2_b32 v[10:11], v22 offset0:214 offset1:247
	s_waitcnt lgkmcnt(0)
	v_cvt_pk_bf16_f32 v43, v10, v11
	v_add_u32_e32 v10, 16, v6
	v_ashrrev_i32_e32 v11, 31, v10
	v_lshlrev_b64 v[10:11], 12, v[10:11]
	v_lshl_add_u64 v[10:11], v[8:9], 0, v[10:11]
	v_add_u32_e32 v6, 24, v6
	global_store_dwordx4 v[10:11], v[40:43], off
	ds_read2_b32 v[10:11], v22 offset0:24 offset1:57
	v_ashrrev_i32_e32 v7, 31, v6
	s_waitcnt lgkmcnt(0)
	v_cvt_pk_bf16_f32 v40, v10, v11
	ds_read2_b32 v[10:11], v22 offset0:90 offset1:123
	v_lshlrev_b64 v[6:7], 12, v[6:7]
	s_waitcnt lgkmcnt(0)
	v_cvt_pk_bf16_f32 v41, v10, v11
	ds_read2_b32 v[10:11], v22 offset0:156 offset1:189
	v_lshl_add_u64 v[6:7], v[8:9], 0, v[6:7]
	s_waitcnt lgkmcnt(0)
	v_cvt_pk_bf16_f32 v42, v10, v11
	ds_read2_b32 v[10:11], v22 offset0:222 offset1:255
	s_waitcnt lgkmcnt(0)
	v_cvt_pk_bf16_f32 v43, v10, v11
	global_store_dwordx4 v[6:7], v[40:43], off
	s_waitcnt lgkmcnt(0)
	s_andn2_b64 exec, exec, s[6:7]
	s_cbranch_execnz .LBB0_1203

.LBB0_2836:
.LBB0_2837:
	v_lshl_or_b32 v144, s18, 8, v135
	v_lshl_add_u32 v186, s16, 8, v134
	v_ashrrev_i32_e32 v145, 31, v144
	v_lshlrev_b64 v[144:145], 2, v[144:145]
	v_ashrrev_i32_e32 v187, 31, v186
	v_lshl_add_u64 v[146:147], s[88:89], 0, v[144:145]
	v_lshlrev_b64 v[148:149], 12, v[186:187]
	v_or_b32_e32 v170, 16, v186
	v_lshl_add_u64 v[166:167], v[146:147], 0, v[148:149]
	v_ashrrev_i32_e32 v171, 31, v170
	v_mov_b64_e32 v[224:225], v[166:167]
	global_load_dwordx4 v[154:157], v[166:167], off
	global_load_dwordx4 v[158:161], v[166:167], off offset:64
	global_load_dwordx4 v[162:165], v[166:167], off offset:512
	s_nop 0
	global_load_dwordx4 v[166:169], v[166:167], off offset:576
	v_lshlrev_b64 v[188:189], 12, v[170:171]
	v_lshl_add_u64 v[182:183], v[146:147], 0, v[188:189]
	global_load_dwordx4 v[170:173], v[182:183], off
	global_load_dwordx4 v[174:177], v[182:183], off offset:64
	global_load_dwordx4 v[178:181], v[182:183], off offset:512
	s_nop 0
	global_load_dwordx4 v[182:185], v[182:183], off offset:576
	v_add_co_u32_e32 v226, vcc, 0x20000, v224
	s_nop 1
	v_addc_co_u32_e32 v227, vcc, 0, v225, vcc
	v_add_co_u32_e32 v228, vcc, 0x30000, v224
	s_nop 1
	v_addc_co_u32_e32 v229, vcc, 0, v225, vcc
	global_load_dwordx4 v[192:195], v[226:227], off
	global_load_dwordx4 v[196:199], v[226:227], off offset:64
	global_load_dwordx4 v[200:203], v[226:227], off offset:512
	global_load_dwordx4 v[204:207], v[226:227], off offset:576
	global_load_dwordx4 v[208:211], v[228:229], off
	global_load_dwordx4 v[212:215], v[228:229], off offset:64
	global_load_dwordx4 v[216:219], v[228:229], off offset:512
	global_load_dwordx4 v[220:223], v[228:229], off offset:576
	v_lshl_add_u64 v[190:191], s[88:89], 0, v[148:149]
	v_lshl_add_u64 v[190:191], v[190:191], 0, v[144:145]
	s_mov_b64 s[20:21], 0x80000
	s_waitcnt vmcnt(8)
	v_pk_add_f32 v[128:129], v[128:129], v[156:157]
	v_pk_add_f32 v[126:127], v[126:127], v[154:155]
	v_pk_add_f32 v[112:113], v[112:113], v[164:165]
	v_pk_add_f32 v[108:109], v[108:109], v[168:169]
	v_pk_add_f32 v[106:107], v[106:107], v[166:167]
	v_pk_add_f32 v[110:111], v[110:111], v[162:163]
	global_store_dwordx4 v[190:191], v[106:109], off offset:576
	global_store_dwordx4 v[190:191], v[110:113], off offset:512
	v_pk_add_f32 v[100:101], v[100:101], v[184:185]
	v_lshl_add_u64 v[106:107], s[88:89], 0, v[188:189]
	v_lshl_add_u64 v[110:111], v[106:107], 0, v[144:145]
	v_pk_add_f32 v[98:99], v[98:99], v[182:183]
	global_store_dwordx4 v[110:111], v[98:101], off offset:576
	v_pk_add_f32 v[108:109], v[120:121], v[172:173]
	v_pk_add_f32 v[106:107], v[118:119], v[170:171]
	v_or_b32_e32 v98, 32, v186
	v_ashrrev_i32_e32 v99, 31, v98
	v_pk_add_f32 v[124:125], v[124:125], v[160:161]
	v_pk_add_f32 v[122:123], v[122:123], v[158:159]
	global_store_dwordx4 v[110:111], v[106:109], off
	v_pk_add_f32 v[104:105], v[104:105], v[180:181]
	v_pk_add_f32 v[102:103], v[102:103], v[178:179]
	v_pk_add_f32 v[108:109], v[116:117], v[176:177]
	v_pk_add_f32 v[106:107], v[114:115], v[174:175]
	v_lshlrev_b64 v[154:155], 12, v[98:99]
	global_store_dwordx4 v[190:191], v[126:129], off
	global_store_dwordx4 v[190:191], v[122:125], off offset:64
	global_store_dwordx4 v[110:111], v[106:109], off offset:64
	global_store_dwordx4 v[110:111], v[102:105], off offset:512
	v_lshl_add_u64 v[110:111], v[146:147], 0, v[154:155]
	v_or_b32_e32 v114, 48, v186
	s_nop 0
	v_ashrrev_i32_e32 v115, 31, v114
	v_lshlrev_b64 v[156:157], 12, v[114:115]
	v_lshl_add_u64 v[126:127], v[146:147], 0, v[156:157]
	s_nop 0
	s_nop 1
	s_waitcnt vmcnt(8)
	v_mov_b64_e32 v[98:99], v[192:193]
	v_mov_b64_e32 v[100:101], v[194:195]
	v_mov_b64_e32 v[102:103], v[196:197]
	v_mov_b64_e32 v[104:105], v[198:199]
	v_mov_b64_e32 v[106:107], v[200:201]
	v_mov_b64_e32 v[108:109], v[202:203]
	v_mov_b64_e32 v[110:111], v[204:205]
	v_mov_b64_e32 v[112:113], v[206:207]
	v_mov_b64_e32 v[114:115], v[208:209]
	v_mov_b64_e32 v[116:117], v[210:211]
	v_mov_b64_e32 v[118:119], v[212:213]
	v_mov_b64_e32 v[120:121], v[214:215]
	v_mov_b64_e32 v[122:123], v[216:217]
	v_mov_b64_e32 v[124:125], v[218:219]
	v_mov_b64_e32 v[126:127], v[220:221]
	v_mov_b64_e32 v[128:129], v[222:223]
	v_add_co_u32_e32 v226, vcc, 0x80000, v224
	s_nop 1
	v_addc_co_u32_e32 v227, vcc, 0, v225, vcc
	v_add_co_u32_e32 v228, vcc, 0x90000, v224
	s_nop 1
	v_addc_co_u32_e32 v229, vcc, 0, v225, vcc
	global_load_dwordx4 v[192:195], v[226:227], off
	global_load_dwordx4 v[196:199], v[226:227], off offset:64
	global_load_dwordx4 v[200:203], v[226:227], off offset:512
	global_load_dwordx4 v[204:207], v[226:227], off offset:576
	global_load_dwordx4 v[208:211], v[228:229], off
	global_load_dwordx4 v[212:215], v[228:229], off offset:64
	global_load_dwordx4 v[216:219], v[228:229], off offset:512
	global_load_dwordx4 v[220:223], v[228:229], off offset:576
	v_lshl_add_u64 v[154:155], s[88:89], 0, v[154:155]
	v_lshl_add_u64 v[154:155], v[154:155], 0, v[144:145]
	v_pk_add_f32 v[96:97], v[96:97], v[100:101]
	v_pk_add_f32 v[94:95], v[94:95], v[98:99]
	v_pk_add_f32 v[80:81], v[80:81], v[108:109]
	v_pk_add_f32 v[76:77], v[76:77], v[112:113]
	v_pk_add_f32 v[74:75], v[74:75], v[110:111]
	v_pk_add_f32 v[78:79], v[78:79], v[106:107]
	global_store_dwordx4 v[154:155], v[74:77], off offset:576
	global_store_dwordx4 v[154:155], v[78:81], off offset:512
	v_pk_add_f32 v[92:93], v[92:93], v[104:105]
	v_lshl_add_u64 v[74:75], s[88:89], 0, v[156:157]
	v_lshl_add_u64 v[78:79], v[74:75], 0, v[144:145]
	v_pk_add_f32 v[76:77], v[88:89], v[116:117]
	v_pk_add_f32 v[74:75], v[86:87], v[114:115]
	v_pk_add_f32 v[90:91], v[90:91], v[102:103]
	global_store_dwordx4 v[78:79], v[74:77], off
	v_pk_add_f32 v[72:73], v[72:73], v[124:125]
	v_pk_add_f32 v[70:71], v[70:71], v[122:123]
	v_pk_add_f32 v[76:77], v[84:85], v[120:121]
	v_pk_add_f32 v[74:75], v[82:83], v[118:119]
	v_pk_add_f32 v[68:69], v[68:69], v[128:129]
	v_pk_add_f32 v[66:67], v[66:67], v[126:127]
	v_lshl_add_u64 v[98:99], v[148:149], 0, s[20:21]
	global_store_dwordx4 v[154:155], v[94:97], off
	global_store_dwordx4 v[154:155], v[90:93], off offset:64
	global_store_dwordx4 v[78:79], v[74:77], off offset:64
	global_store_dwordx4 v[78:79], v[70:73], off offset:512
	global_store_dwordx4 v[78:79], v[66:69], off offset:576
	v_lshl_add_u64 v[78:79], v[146:147], 0, v[98:99]
	s_nop 0
	s_mov_b64 s[20:21], 0x90000
	v_lshl_add_u64 v[100:101], v[148:149], 0, s[20:21]
	v_lshl_add_u64 v[94:95], v[146:147], 0, v[100:101]
	s_nop 0
	s_nop 1
	s_waitcnt vmcnt(8)
	v_mov_b64_e32 v[66:67], v[192:193]
	v_mov_b64_e32 v[68:69], v[194:195]
	v_mov_b64_e32 v[70:71], v[196:197]
	v_mov_b64_e32 v[72:73], v[198:199]
	v_mov_b64_e32 v[74:75], v[200:201]
	v_mov_b64_e32 v[76:77], v[202:203]
	v_mov_b64_e32 v[78:79], v[204:205]
	v_mov_b64_e32 v[80:81], v[206:207]
	v_mov_b64_e32 v[82:83], v[208:209]
	v_mov_b64_e32 v[84:85], v[210:211]
	v_mov_b64_e32 v[86:87], v[212:213]
	v_mov_b64_e32 v[88:89], v[214:215]
	v_mov_b64_e32 v[90:91], v[216:217]
	v_mov_b64_e32 v[92:93], v[218:219]
	v_mov_b64_e32 v[94:95], v[220:221]
	v_mov_b64_e32 v[96:97], v[222:223]
	v_add_co_u32_e32 v226, vcc, 0xa0000, v224
	s_nop 1
	v_addc_co_u32_e32 v227, vcc, 0, v225, vcc
	v_add_co_u32_e32 v228, vcc, 0xb0000, v224
	s_nop 1
	v_addc_co_u32_e32 v229, vcc, 0, v225, vcc
	global_load_dwordx4 v[192:195], v[226:227], off
	global_load_dwordx4 v[196:199], v[226:227], off offset:64
	global_load_dwordx4 v[200:203], v[226:227], off offset:512
	global_load_dwordx4 v[204:207], v[226:227], off offset:576
	global_load_dwordx4 v[208:211], v[228:229], off
	global_load_dwordx4 v[212:215], v[228:229], off offset:64
	global_load_dwordx4 v[216:219], v[228:229], off offset:512
	global_load_dwordx4 v[220:223], v[228:229], off offset:576
	v_lshl_add_u64 v[98:99], s[88:89], 0, v[98:99]
	v_lshl_add_u64 v[98:99], v[98:99], 0, v[144:145]
	s_mov_b64 s[20:21], 0xa0000
	v_pk_add_f32 v[64:65], v[64:65], v[68:69]
	v_pk_add_f32 v[62:63], v[62:63], v[66:67]
	v_pk_add_f32 v[48:49], v[48:49], v[76:77]
	v_pk_add_f32 v[44:45], v[44:45], v[80:81]
	v_pk_add_f32 v[42:43], v[42:43], v[78:79]
	v_pk_add_f32 v[46:47], v[46:47], v[74:75]
	global_store_dwordx4 v[98:99], v[42:45], off offset:576
	global_store_dwordx4 v[98:99], v[46:49], off offset:512
	v_pk_add_f32 v[60:61], v[60:61], v[72:73]
	v_lshl_add_u64 v[42:43], s[88:89], 0, v[100:101]
	v_lshl_add_u64 v[46:47], v[42:43], 0, v[144:145]
	v_pk_add_f32 v[44:45], v[56:57], v[84:85]
	v_pk_add_f32 v[42:43], v[54:55], v[82:83]
	v_pk_add_f32 v[58:59], v[58:59], v[70:71]
	global_store_dwordx4 v[46:47], v[42:45], off
	v_pk_add_f32 v[40:41], v[40:41], v[92:93]
	v_pk_add_f32 v[38:39], v[38:39], v[90:91]
	v_pk_add_f32 v[44:45], v[52:53], v[88:89]
	v_pk_add_f32 v[42:43], v[50:51], v[86:87]
	v_pk_add_f32 v[36:37], v[36:37], v[96:97]
	v_pk_add_f32 v[34:35], v[34:35], v[94:95]
	v_lshl_add_u64 v[66:67], v[148:149], 0, s[20:21]
	global_store_dwordx4 v[98:99], v[62:65], off
	global_store_dwordx4 v[98:99], v[58:61], off offset:64
	global_store_dwordx4 v[46:47], v[42:45], off offset:64
	global_store_dwordx4 v[46:47], v[38:41], off offset:512
	global_store_dwordx4 v[46:47], v[34:37], off offset:576
	s_mov_b64 s[20:21], 0xb0000
	v_lshl_add_u64 v[68:69], v[148:149], 0, s[20:21]
	v_lshl_add_u64 v[34:35], v[146:147], 0, v[66:67]
	s_nop 0
	v_lshl_add_u64 v[62:63], v[146:147], 0, v[68:69]
	s_nop 0
	s_nop 1
	s_waitcnt vmcnt(8)
	v_mov_b64_e32 v[46:47], v[192:193]
	v_mov_b64_e32 v[48:49], v[194:195]
	v_mov_b64_e32 v[42:43], v[196:197]
	v_mov_b64_e32 v[44:45], v[198:199]
	v_mov_b64_e32 v[38:39], v[200:201]
	v_mov_b64_e32 v[40:41], v[202:203]
	v_mov_b64_e32 v[34:35], v[204:205]
	v_mov_b64_e32 v[36:37], v[206:207]
	v_mov_b64_e32 v[58:59], v[208:209]
	v_mov_b64_e32 v[60:61], v[210:211]
	v_mov_b64_e32 v[54:55], v[212:213]
	v_mov_b64_e32 v[56:57], v[214:215]
	v_mov_b64_e32 v[50:51], v[216:217]
	v_mov_b64_e32 v[52:53], v[218:219]
	v_mov_b64_e32 v[62:63], v[220:221]
	v_mov_b64_e32 v[64:65], v[222:223]
	v_lshl_add_u64 v[66:67], s[88:89], 0, v[66:67]
	v_lshl_add_u64 v[66:67], v[66:67], 0, v[144:145]
	v_pk_add_f32 v[32:33], v[32:33], v[48:49]
	v_pk_add_f32 v[30:31], v[30:31], v[46:47]
	v_pk_add_f32 v[20:21], v[20:21], v[40:41]
	v_pk_add_f32 v[12:13], v[12:13], v[36:37]
	v_pk_add_f32 v[10:11], v[10:11], v[34:35]
	v_pk_add_f32 v[18:19], v[18:19], v[38:39]
	global_store_dwordx4 v[66:67], v[10:13], off offset:576
	global_store_dwordx4 v[66:67], v[18:21], off offset:512
	v_pk_add_f32 v[28:29], v[28:29], v[44:45]
	v_lshl_add_u64 v[10:11], s[88:89], 0, v[68:69]
	v_lshl_add_u64 v[18:19], v[10:11], 0, v[144:145]
	v_pk_add_f32 v[12:13], v[24:25], v[60:61]
	v_pk_add_f32 v[10:11], v[22:23], v[58:59]
	v_pk_add_f32 v[26:27], v[26:27], v[42:43]
	global_store_dwordx4 v[18:19], v[10:13], off
	v_pk_add_f32 v[8:9], v[8:9], v[52:53]
	v_pk_add_f32 v[6:7], v[6:7], v[50:51]
	v_pk_add_f32 v[12:13], v[16:17], v[56:57]
	v_pk_add_f32 v[10:11], v[14:15], v[54:55]
	v_pk_add_f32 v[4:5], v[4:5], v[64:65]
	v_pk_add_f32 v[2:3], v[2:3], v[62:63]
	global_store_dwordx4 v[66:67], v[30:33], off
	global_store_dwordx4 v[66:67], v[26:29], off offset:64
	global_store_dwordx4 v[18:19], v[10:13], off offset:64
	global_store_dwordx4 v[18:19], v[6:9], off offset:512
	global_store_dwordx4 v[18:19], v[2:5], off offset:576
	s_branch .LBB0_2822

.LBB0_3517:
	v_lshl_or_b32 v144, s26, 8, v135
	v_lshl_add_u32 v186, s24, 8, v134
	v_ashrrev_i32_e32 v145, 31, v144
	v_lshlrev_b64 v[144:145], 2, v[144:145]
	v_ashrrev_i32_e32 v187, 31, v186
	v_lshl_add_u64 v[146:147], s[88:89], 0, v[144:145]
	v_lshlrev_b64 v[148:149], 12, v[186:187]
	v_or_b32_e32 v170, 16, v186
	v_lshl_add_u64 v[166:167], v[146:147], 0, v[148:149]
	v_ashrrev_i32_e32 v171, 31, v170
	v_mov_b64_e32 v[224:225], v[166:167]
	global_load_dwordx4 v[154:157], v[166:167], off
	global_load_dwordx4 v[158:161], v[166:167], off offset:64
	global_load_dwordx4 v[162:165], v[166:167], off offset:512
	s_nop 0
	global_load_dwordx4 v[166:169], v[166:167], off offset:576
	v_lshlrev_b64 v[188:189], 12, v[170:171]
	v_lshl_add_u64 v[182:183], v[146:147], 0, v[188:189]
	global_load_dwordx4 v[170:173], v[182:183], off
	global_load_dwordx4 v[174:177], v[182:183], off offset:64
	global_load_dwordx4 v[178:181], v[182:183], off offset:512
	s_nop 0
	global_load_dwordx4 v[182:185], v[182:183], off offset:576
	v_add_co_u32_e32 v226, vcc, 0x20000, v224
	s_nop 1
	v_addc_co_u32_e32 v227, vcc, 0, v225, vcc
	v_add_co_u32_e32 v228, vcc, 0x30000, v224
	s_nop 1
	v_addc_co_u32_e32 v229, vcc, 0, v225, vcc
	global_load_dwordx4 v[192:195], v[226:227], off
	global_load_dwordx4 v[196:199], v[226:227], off offset:64
	global_load_dwordx4 v[200:203], v[226:227], off offset:512
	global_load_dwordx4 v[204:207], v[226:227], off offset:576
	global_load_dwordx4 v[208:211], v[228:229], off
	global_load_dwordx4 v[212:215], v[228:229], off offset:64
	global_load_dwordx4 v[216:219], v[228:229], off offset:512
	global_load_dwordx4 v[220:223], v[228:229], off offset:576
	v_lshl_add_u64 v[190:191], s[88:89], 0, v[148:149]
	v_lshl_add_u64 v[190:191], v[190:191], 0, v[144:145]
	s_waitcnt vmcnt(8)
	v_pk_add_f32 v[128:129], v[128:129], v[156:157]
	v_pk_add_f32 v[126:127], v[126:127], v[154:155]
	v_pk_add_f32 v[112:113], v[112:113], v[164:165]
	v_pk_add_f32 v[108:109], v[108:109], v[168:169]
	v_pk_add_f32 v[106:107], v[106:107], v[166:167]
	v_pk_add_f32 v[110:111], v[110:111], v[162:163]
	global_store_dwordx4 v[190:191], v[106:109], off offset:576
	global_store_dwordx4 v[190:191], v[110:113], off offset:512
	v_pk_add_f32 v[100:101], v[100:101], v[184:185]
	v_lshl_add_u64 v[106:107], s[88:89], 0, v[188:189]
	v_lshl_add_u64 v[110:111], v[106:107], 0, v[144:145]
	v_pk_add_f32 v[98:99], v[98:99], v[182:183]
	global_store_dwordx4 v[110:111], v[98:101], off offset:576
	v_pk_add_f32 v[108:109], v[120:121], v[172:173]
	v_pk_add_f32 v[106:107], v[118:119], v[170:171]
	v_or_b32_e32 v98, 32, v186
	v_ashrrev_i32_e32 v99, 31, v98
	v_pk_add_f32 v[124:125], v[124:125], v[160:161]
	v_pk_add_f32 v[122:123], v[122:123], v[158:159]
	global_store_dwordx4 v[110:111], v[106:109], off
	v_pk_add_f32 v[104:105], v[104:105], v[180:181]
	v_pk_add_f32 v[102:103], v[102:103], v[178:179]
	v_pk_add_f32 v[108:109], v[116:117], v[176:177]
	v_pk_add_f32 v[106:107], v[114:115], v[174:175]
	v_lshlrev_b64 v[154:155], 12, v[98:99]
	global_store_dwordx4 v[190:191], v[126:129], off
	global_store_dwordx4 v[190:191], v[122:125], off offset:64
	global_store_dwordx4 v[110:111], v[106:109], off offset:64
	global_store_dwordx4 v[110:111], v[102:105], off offset:512
	v_lshl_add_u64 v[110:111], v[146:147], 0, v[154:155]
	v_or_b32_e32 v114, 48, v186
	s_nop 0
	v_ashrrev_i32_e32 v115, 31, v114
	v_lshlrev_b64 v[156:157], 12, v[114:115]
	v_lshl_add_u64 v[126:127], v[146:147], 0, v[156:157]
	s_nop 0
	s_nop 1
	s_waitcnt vmcnt(8)
	v_mov_b64_e32 v[98:99], v[192:193]
	v_mov_b64_e32 v[100:101], v[194:195]
	v_mov_b64_e32 v[102:103], v[196:197]
	v_mov_b64_e32 v[104:105], v[198:199]
	v_mov_b64_e32 v[106:107], v[200:201]
	v_mov_b64_e32 v[108:109], v[202:203]
	v_mov_b64_e32 v[110:111], v[204:205]
	v_mov_b64_e32 v[112:113], v[206:207]
	v_mov_b64_e32 v[114:115], v[208:209]
	v_mov_b64_e32 v[116:117], v[210:211]
	v_mov_b64_e32 v[118:119], v[212:213]
	v_mov_b64_e32 v[120:121], v[214:215]
	v_mov_b64_e32 v[122:123], v[216:217]
	v_mov_b64_e32 v[124:125], v[218:219]
	v_mov_b64_e32 v[126:127], v[220:221]
	v_mov_b64_e32 v[128:129], v[222:223]
	v_add_co_u32_e32 v226, vcc, 0x80000, v224
	s_nop 1
	v_addc_co_u32_e32 v227, vcc, 0, v225, vcc
	v_add_co_u32_e32 v228, vcc, 0x90000, v224
	s_nop 1
	v_addc_co_u32_e32 v229, vcc, 0, v225, vcc
	global_load_dwordx4 v[192:195], v[226:227], off
	global_load_dwordx4 v[196:199], v[226:227], off offset:64
	global_load_dwordx4 v[200:203], v[226:227], off offset:512
	global_load_dwordx4 v[204:207], v[226:227], off offset:576
	global_load_dwordx4 v[208:211], v[228:229], off
	global_load_dwordx4 v[212:215], v[228:229], off offset:64
	global_load_dwordx4 v[216:219], v[228:229], off offset:512
	global_load_dwordx4 v[220:223], v[228:229], off offset:576
	v_lshl_add_u64 v[154:155], s[88:89], 0, v[154:155]
	v_lshl_add_u64 v[154:155], v[154:155], 0, v[144:145]
	v_pk_add_f32 v[96:97], v[96:97], v[100:101]
	v_pk_add_f32 v[94:95], v[94:95], v[98:99]
	v_pk_add_f32 v[80:81], v[80:81], v[108:109]
	v_pk_add_f32 v[76:77], v[76:77], v[112:113]
	v_pk_add_f32 v[74:75], v[74:75], v[110:111]
	v_pk_add_f32 v[78:79], v[78:79], v[106:107]
	global_store_dwordx4 v[154:155], v[74:77], off offset:576
	global_store_dwordx4 v[154:155], v[78:81], off offset:512
	v_pk_add_f32 v[92:93], v[92:93], v[104:105]
	v_lshl_add_u64 v[74:75], s[88:89], 0, v[156:157]
	v_lshl_add_u64 v[78:79], v[74:75], 0, v[144:145]
	v_pk_add_f32 v[76:77], v[88:89], v[116:117]
	v_pk_add_f32 v[74:75], v[86:87], v[114:115]
	v_pk_add_f32 v[90:91], v[90:91], v[102:103]
	global_store_dwordx4 v[78:79], v[74:77], off
	v_pk_add_f32 v[72:73], v[72:73], v[124:125]
	v_pk_add_f32 v[70:71], v[70:71], v[122:123]
	v_pk_add_f32 v[76:77], v[84:85], v[120:121]
	v_pk_add_f32 v[74:75], v[82:83], v[118:119]
	v_pk_add_f32 v[68:69], v[68:69], v[128:129]
	v_pk_add_f32 v[66:67], v[66:67], v[126:127]
	v_lshl_add_u64 v[98:99], v[148:149], 0, s[4:5]
	global_store_dwordx4 v[154:155], v[94:97], off
	global_store_dwordx4 v[154:155], v[90:93], off offset:64
	global_store_dwordx4 v[78:79], v[74:77], off offset:64
	global_store_dwordx4 v[78:79], v[70:73], off offset:512
	global_store_dwordx4 v[78:79], v[66:69], off offset:576
	v_lshl_add_u64 v[78:79], v[146:147], 0, v[98:99]
	s_nop 0
	v_lshl_add_u64 v[100:101], v[148:149], 0, s[6:7]
	v_lshl_add_u64 v[94:95], v[146:147], 0, v[100:101]
	s_nop 0
	s_nop 1
	s_waitcnt vmcnt(8)
	v_mov_b64_e32 v[66:67], v[192:193]
	v_mov_b64_e32 v[68:69], v[194:195]
	v_mov_b64_e32 v[70:71], v[196:197]
	v_mov_b64_e32 v[72:73], v[198:199]
	v_mov_b64_e32 v[74:75], v[200:201]
	v_mov_b64_e32 v[76:77], v[202:203]
	v_mov_b64_e32 v[78:79], v[204:205]
	v_mov_b64_e32 v[80:81], v[206:207]
	v_mov_b64_e32 v[82:83], v[208:209]
	v_mov_b64_e32 v[84:85], v[210:211]
	v_mov_b64_e32 v[86:87], v[212:213]
	v_mov_b64_e32 v[88:89], v[214:215]
	v_mov_b64_e32 v[90:91], v[216:217]
	v_mov_b64_e32 v[92:93], v[218:219]
	v_mov_b64_e32 v[94:95], v[220:221]
	v_mov_b64_e32 v[96:97], v[222:223]
	v_add_co_u32_e32 v226, vcc, 0xa0000, v224
	s_nop 1
	v_addc_co_u32_e32 v227, vcc, 0, v225, vcc
	v_add_co_u32_e32 v228, vcc, 0xb0000, v224
	s_nop 1
	v_addc_co_u32_e32 v229, vcc, 0, v225, vcc
	global_load_dwordx4 v[192:195], v[226:227], off
	global_load_dwordx4 v[196:199], v[226:227], off offset:64
	global_load_dwordx4 v[200:203], v[226:227], off offset:512
	global_load_dwordx4 v[204:207], v[226:227], off offset:576
	global_load_dwordx4 v[208:211], v[228:229], off
	global_load_dwordx4 v[212:215], v[228:229], off offset:64
	global_load_dwordx4 v[216:219], v[228:229], off offset:512
	global_load_dwordx4 v[220:223], v[228:229], off offset:576
	v_lshl_add_u64 v[98:99], s[88:89], 0, v[98:99]
	v_lshl_add_u64 v[98:99], v[98:99], 0, v[144:145]
	v_pk_add_f32 v[64:65], v[64:65], v[68:69]
	v_pk_add_f32 v[62:63], v[62:63], v[66:67]
	v_pk_add_f32 v[48:49], v[48:49], v[76:77]
	v_pk_add_f32 v[44:45], v[44:45], v[80:81]
	v_pk_add_f32 v[42:43], v[42:43], v[78:79]
	v_pk_add_f32 v[46:47], v[46:47], v[74:75]
	global_store_dwordx4 v[98:99], v[42:45], off offset:576
	global_store_dwordx4 v[98:99], v[46:49], off offset:512
	global_store_dwordx4 v[98:99], v[62:65], off
	v_lshl_add_u64 v[42:43], s[88:89], 0, v[100:101]
	v_lshl_add_u64 v[46:47], v[42:43], 0, v[144:145]
	v_pk_add_f32 v[44:45], v[56:57], v[84:85]
	v_pk_add_f32 v[42:43], v[54:55], v[82:83]
	v_pk_add_f32 v[60:61], v[60:61], v[72:73]
	v_pk_add_f32 v[58:59], v[58:59], v[70:71]
	global_store_dwordx4 v[46:47], v[42:45], off
	v_pk_add_f32 v[40:41], v[40:41], v[92:93]
	v_pk_add_f32 v[38:39], v[38:39], v[90:91]
	v_pk_add_f32 v[44:45], v[52:53], v[88:89]
	v_pk_add_f32 v[42:43], v[50:51], v[86:87]
	v_pk_add_f32 v[36:37], v[36:37], v[96:97]
	v_pk_add_f32 v[34:35], v[34:35], v[94:95]
	v_lshl_add_u64 v[64:65], v[148:149], 0, s[8:9]
	global_store_dwordx4 v[98:99], v[58:61], off offset:64
	global_store_dwordx4 v[46:47], v[42:45], off offset:64
	global_store_dwordx4 v[46:47], v[38:41], off offset:512
	global_store_dwordx4 v[46:47], v[34:37], off offset:576
	v_lshl_add_u64 v[62:63], v[148:149], 0, s[10:11]
	v_lshl_add_u64 v[66:67], v[146:147], 0, v[62:63]
	v_lshl_add_u64 v[34:35], v[146:147], 0, v[64:65]
	s_nop 0
	s_nop 0
	s_nop 0
	s_nop 1
	s_waitcnt vmcnt(8)
	v_mov_b64_e32 v[46:47], v[192:193]
	v_mov_b64_e32 v[48:49], v[194:195]
	v_mov_b64_e32 v[42:43], v[196:197]
	v_mov_b64_e32 v[44:45], v[198:199]
	v_mov_b64_e32 v[38:39], v[200:201]
	v_mov_b64_e32 v[40:41], v[202:203]
	v_mov_b64_e32 v[34:35], v[204:205]
	v_mov_b64_e32 v[36:37], v[206:207]
	v_mov_b64_e32 v[58:59], v[208:209]
	v_mov_b64_e32 v[60:61], v[210:211]
	v_mov_b64_e32 v[54:55], v[212:213]
	v_mov_b64_e32 v[56:57], v[214:215]
	v_mov_b64_e32 v[50:51], v[216:217]
	v_mov_b64_e32 v[52:53], v[218:219]
	v_mov_b64_e32 v[66:67], v[220:221]
	v_mov_b64_e32 v[68:69], v[222:223]
	v_lshl_add_u64 v[64:65], s[88:89], 0, v[64:65]
	v_lshl_add_u64 v[64:65], v[64:65], 0, v[144:145]
	v_pk_add_f32 v[32:33], v[32:33], v[48:49]
	v_pk_add_f32 v[30:31], v[30:31], v[46:47]
	v_pk_add_f32 v[20:21], v[20:21], v[40:41]
	v_pk_add_f32 v[12:13], v[12:13], v[36:37]
	v_pk_add_f32 v[10:11], v[10:11], v[34:35]
	v_pk_add_f32 v[18:19], v[18:19], v[38:39]
	global_store_dwordx4 v[64:65], v[10:13], off offset:576
	global_store_dwordx4 v[64:65], v[18:21], off offset:512
	v_pk_add_f32 v[28:29], v[28:29], v[44:45]
	v_lshl_add_u64 v[10:11], s[88:89], 0, v[62:63]
	v_lshl_add_u64 v[18:19], v[10:11], 0, v[144:145]
	v_pk_add_f32 v[12:13], v[24:25], v[60:61]
	v_pk_add_f32 v[10:11], v[22:23], v[58:59]
	v_pk_add_f32 v[26:27], v[26:27], v[42:43]
	global_store_dwordx4 v[18:19], v[10:13], off
	v_pk_add_f32 v[8:9], v[8:9], v[52:53]
	v_pk_add_f32 v[6:7], v[6:7], v[50:51]
	v_pk_add_f32 v[12:13], v[16:17], v[56:57]
	v_pk_add_f32 v[10:11], v[14:15], v[54:55]
	v_pk_add_f32 v[4:5], v[4:5], v[68:69]
	v_pk_add_f32 v[2:3], v[2:3], v[66:67]
	global_store_dwordx4 v[64:65], v[30:33], off
	global_store_dwordx4 v[64:65], v[26:29], off offset:64
	global_store_dwordx4 v[18:19], v[10:13], off offset:64
	global_store_dwordx4 v[18:19], v[6:9], off offset:512
	global_store_dwordx4 v[18:19], v[2:5], off offset:576
	s_branch .LBB0_3502
